# GEMM loops: back edge rotated (doc 7.11) - loop-back s_barrier is the loop head shared with the lag half's entry barrier; size-neutral
# speedup vs baseline: 1.0055x; 1.0055x over previous
.LBB0_127:
	s_ashr_i32 s13, s12, 31
	s_lshl_b64 s[0:1], s[12:13], 19
	s_add_u32 s42, s6, s0
	v_cmp_lt_i64_e32 vcc, s[34:35], v[236:237]
	s_addc_u32 s43, s7, s1
	s_and_b64 s[0:1], vcc, exec
	s_cselect_b32 s0, s43, s19
	s_cselect_b32 s1, s42, s18
	s_ashr_i32 s31, s30, 31
	s_lshl_b64 s[24:25], s[30:31], 19
	s_add_u32 s44, s16, s24
	s_addc_u32 s45, s17, s25
	s_and_b64 s[24:25], vcc, exec
	s_cselect_b32 s13, s45, s15
	s_cselect_b32 s24, s44, s14
	s_add_u32 vcc_lo, s18, 0x40080
	s_addc_u32 vcc_hi, s19, 0
	s_add_u32 s25, s14, 0x100
	v_mov_b32_e32 v0, 0
	s_addc_u32 s31, s15, 0
	s_mov_b32 s34, -2
	v_mov_b32_e32 v1, v0
	v_mov_b32_e32 v2, v0
	v_mov_b32_e32 v3, v0
	v_mov_b32_e32 v4, v0
	v_mov_b32_e32 v5, v0
	v_mov_b32_e32 v6, v0
	v_mov_b32_e32 v7, v0
	v_mov_b32_e32 v16, v0
	v_mov_b32_e32 v17, v0
	v_mov_b32_e32 v18, v0
	v_mov_b32_e32 v19, v0
	v_mov_b32_e32 v20, v0
	v_mov_b32_e32 v21, v0
	v_mov_b32_e32 v22, v0
	v_mov_b32_e32 v23, v0
	v_mov_b32_e32 v32, v0
	v_mov_b32_e32 v33, v0
	v_mov_b32_e32 v34, v0
	v_mov_b32_e32 v35, v0
	v_mov_b32_e32 v36, v0
	v_mov_b32_e32 v37, v0
	v_mov_b32_e32 v38, v0
	v_mov_b32_e32 v39, v0
	v_mov_b32_e32 v48, v0
	v_mov_b32_e32 v49, v0
	v_mov_b32_e32 v50, v0
	v_mov_b32_e32 v51, v0
	v_mov_b32_e32 v52, v0
	v_mov_b32_e32 v53, v0
	v_mov_b32_e32 v54, v0
	v_mov_b32_e32 v55, v0
	v_mov_b32_e32 v8, v0
	v_mov_b32_e32 v9, v0
	v_mov_b32_e32 v10, v0
	v_mov_b32_e32 v11, v0
	v_mov_b32_e32 v12, v0
	v_mov_b32_e32 v13, v0
	v_mov_b32_e32 v14, v0
	v_mov_b32_e32 v15, v0
	v_mov_b32_e32 v24, v0
	v_mov_b32_e32 v25, v0
	v_mov_b32_e32 v26, v0
	v_mov_b32_e32 v27, v0
	v_mov_b32_e32 v28, v0
	v_mov_b32_e32 v29, v0
	v_mov_b32_e32 v30, v0
	v_mov_b32_e32 v31, v0
	v_mov_b32_e32 v40, v0
	v_mov_b32_e32 v41, v0
	v_mov_b32_e32 v42, v0
	v_mov_b32_e32 v43, v0
	v_mov_b32_e32 v44, v0
	v_mov_b32_e32 v45, v0
	v_mov_b32_e32 v46, v0
	v_mov_b32_e32 v47, v0
	v_mov_b32_e32 v56, v0
	v_mov_b32_e32 v57, v0
	v_mov_b32_e32 v58, v0
	v_mov_b32_e32 v59, v0
	v_mov_b32_e32 v60, v0
	v_mov_b32_e32 v61, v0
	v_mov_b32_e32 v62, v0
	v_mov_b32_e32 v63, v0
	v_mov_b32_e32 v64, v0
	v_mov_b32_e32 v65, v0
	v_mov_b32_e32 v66, v0
	v_mov_b32_e32 v67, v0
	v_mov_b32_e32 v68, v0
	v_mov_b32_e32 v69, v0
	v_mov_b32_e32 v70, v0
	v_mov_b32_e32 v71, v0
	v_mov_b32_e32 v80, v0
	v_mov_b32_e32 v81, v0
	v_mov_b32_e32 v82, v0
	v_mov_b32_e32 v83, v0
	v_mov_b32_e32 v84, v0
	v_mov_b32_e32 v85, v0
	v_mov_b32_e32 v86, v0
	v_mov_b32_e32 v87, v0
	v_mov_b32_e32 v96, v0
	v_mov_b32_e32 v97, v0
	v_mov_b32_e32 v98, v0
	v_mov_b32_e32 v99, v0
	v_mov_b32_e32 v100, v0
	v_mov_b32_e32 v101, v0
	v_mov_b32_e32 v102, v0
	v_mov_b32_e32 v103, v0
	v_mov_b32_e32 v112, v0
	v_mov_b32_e32 v113, v0
	v_mov_b32_e32 v114, v0
	v_mov_b32_e32 v115, v0
	v_mov_b32_e32 v116, v0
	v_mov_b32_e32 v117, v0
	v_mov_b32_e32 v118, v0
	v_mov_b32_e32 v119, v0
	v_mov_b32_e32 v72, v0
	v_mov_b32_e32 v73, v0
	v_mov_b32_e32 v74, v0
	v_mov_b32_e32 v75, v0
	v_mov_b32_e32 v76, v0
	v_mov_b32_e32 v77, v0
	v_mov_b32_e32 v78, v0
	v_mov_b32_e32 v79, v0
	v_mov_b32_e32 v88, v0
	v_mov_b32_e32 v89, v0
	v_mov_b32_e32 v90, v0
	v_mov_b32_e32 v91, v0
	v_mov_b32_e32 v92, v0
	v_mov_b32_e32 v93, v0
	v_mov_b32_e32 v94, v0
	v_mov_b32_e32 v95, v0
	v_mov_b32_e32 v104, v0
	v_mov_b32_e32 v105, v0
	v_mov_b32_e32 v106, v0
	v_mov_b32_e32 v107, v0
	v_mov_b32_e32 v108, v0
	v_mov_b32_e32 v109, v0
	v_mov_b32_e32 v110, v0
	v_mov_b32_e32 v111, v0
	v_mov_b32_e32 v120, v0
	v_mov_b32_e32 v121, v0
	v_mov_b32_e32 v122, v0
	v_mov_b32_e32 v123, v0
	v_mov_b32_e32 v124, v0
	v_mov_b32_e32 v125, v0
	v_mov_b32_e32 v126, v0
	v_mov_b32_e32 v127, v0
	s_cmpk_gt_u32 s50, 0xff
	s_cbranch_scc0 .Lgout_enter
	s_setprio 1

.Lgout_enter:
.LBB0_128:
	s_add_u32 s14, vcc_lo, 0xfffc0080
	s_addc_u32 s15, vcc_hi, -1
	s_add_i32 s20, 16, 0x10000
	v_add_u32_e32 v130, s20, v160
	ds_read_b128 v[154:157], v130
	ds_read_b128 v[164:167], v130 offset:1024
	ds_read_b128 v[168:171], v130 offset:2048
	ds_read_b128 v[172:175], v130 offset:3072
	s_cmp_eq_u32 s34, 12
	s_cselect_b32 s19, s0, s15
	s_cselect_b32 s18, s1, s14
	s_cselect_b32 s15, s13, s31
	s_cselect_b32 s14, s24, s25
	v_lshl_add_u64 v[130:131], vcc, 0, v[150:151]
	s_add_i32 m0, s9, 0xc000
	ds_read_b128 v[176:179], v162
	ds_read_b128 v[180:183], v162 offset:1024
	ds_read_b128 v[184:187], v162 offset:2048
	ds_read_b128 v[188:191], v162 offset:3072
	ds_read_b128 v[192:195], v162 offset:4096
	ds_read_b128 v[196:199], v162 offset:5120
	ds_read_b128 v[200:203], v162 offset:6144
	ds_read_b128 v[204:207], v162 offset:7168
	global_load_lds_dwordx4 v[130:131], off
	v_lshl_add_u64 v[130:131], vcc, 0, v[152:153]
	s_add_i32 m0, s9, 0xe000
	s_nop 0
	global_load_lds_dwordx4 v[130:131], off
	s_add_i32 s35, 16, 0x14000
	v_add_u32_e32 v130, s35, v160
	ds_read_b128 v[208:211], v130
	ds_read_b128 v[212:215], v130 offset:1024
	ds_read_b128 v[216:219], v130 offset:2048
	ds_read_b128 v[220:223], v130 offset:3072
	s_waitcnt vmcnt(8) lgkmcnt(0)
	s_barrier
	v_mfma_f32_16x16x32_bf16 v[124:127], v[154:157], v[176:179], v[124:127]
	v_mfma_f32_16x16x32_bf16 v[120:123], v[168:171], v[176:179], v[120:123]
	v_mfma_f32_16x16x32_bf16 v[108:111], v[154:157], v[184:187], v[108:111]
	v_mfma_f32_16x16x32_bf16 v[104:107], v[168:171], v[184:187], v[104:107]
	v_mfma_f32_16x16x32_bf16 v[92:95], v[154:157], v[192:195], v[92:95]
	v_mfma_f32_16x16x32_bf16 v[88:91], v[168:171], v[192:195], v[88:91]
	v_mfma_f32_16x16x32_bf16 v[76:79], v[154:157], v[200:203], v[76:79]
	v_mfma_f32_16x16x32_bf16 v[72:75], v[168:171], v[200:203], v[72:75]
	v_mfma_f32_16x16x32_bf16 v[124:127], v[164:167], v[180:183], v[124:127]
	v_mfma_f32_16x16x32_bf16 v[120:123], v[172:175], v[180:183], v[120:123]
	v_mfma_f32_16x16x32_bf16 v[108:111], v[164:167], v[188:191], v[108:111]
	v_mfma_f32_16x16x32_bf16 v[104:107], v[172:175], v[188:191], v[104:107]
	v_mfma_f32_16x16x32_bf16 v[92:95], v[164:167], v[196:199], v[92:95]
	v_mfma_f32_16x16x32_bf16 v[88:91], v[172:175], v[196:199], v[88:91]
	v_mfma_f32_16x16x32_bf16 v[76:79], v[164:167], v[204:207], v[76:79]
	v_mfma_f32_16x16x32_bf16 v[72:75], v[172:175], v[204:207], v[72:75]
	v_mfma_f32_16x16x32_bf16 v[116:119], v[208:211], v[176:179], v[116:119]
	v_mfma_f32_16x16x32_bf16 v[112:115], v[216:219], v[176:179], v[112:115]
	v_mfma_f32_16x16x32_bf16 v[100:103], v[208:211], v[184:187], v[100:103]
	v_mfma_f32_16x16x32_bf16 v[96:99], v[216:219], v[184:187], v[96:99]
	v_mfma_f32_16x16x32_bf16 v[84:87], v[208:211], v[192:195], v[84:87]
	v_mfma_f32_16x16x32_bf16 v[80:83], v[216:219], v[192:195], v[80:83]
	v_mfma_f32_16x16x32_bf16 v[68:71], v[208:211], v[200:203], v[68:71]
	v_mfma_f32_16x16x32_bf16 v[64:67], v[216:219], v[200:203], v[64:67]
	v_mfma_f32_16x16x32_bf16 v[116:119], v[212:215], v[180:183], v[116:119]
	v_mfma_f32_16x16x32_bf16 v[112:115], v[220:223], v[180:183], v[112:115]
	v_mfma_f32_16x16x32_bf16 v[100:103], v[212:215], v[188:191], v[100:103]
	v_mfma_f32_16x16x32_bf16 v[96:99], v[220:223], v[188:191], v[96:99]
	v_mfma_f32_16x16x32_bf16 v[84:87], v[212:215], v[196:199], v[84:87]
	v_mfma_f32_16x16x32_bf16 v[80:83], v[220:223], v[196:199], v[80:83]
	v_mfma_f32_16x16x32_bf16 v[68:71], v[212:215], v[204:207], v[68:71]
	v_mfma_f32_16x16x32_bf16 v[64:67], v[220:223], v[204:207], v[64:67]
	s_barrier
	ds_read_b128 v[176:179], v162 offset:16384
	ds_read_b128 v[180:183], v162 offset:17408
	ds_read_b128 v[184:187], v162 offset:18432
	ds_read_b128 v[188:191], v162 offset:19456
	ds_read_b128 v[192:195], v162 offset:20480
	ds_read_b128 v[196:199], v162 offset:21504
	ds_read_b128 v[200:203], v162 offset:22528
	ds_read_b128 v[204:207], v162 offset:23552
	s_add_i32 s20, s20, s5
	v_lshl_add_u64 v[130:131], s[14:15], 0, v[128:129]
	s_mov_b32 m0, s20
	v_lshl_add_u64 v[132:133], s[14:15], 0, v[148:149]
	global_load_lds_dwordx4 v[130:131], off
	s_add_i32 m0, s20, 0x2000
	s_nop 0
	global_load_lds_dwordx4 v[132:133], off
	s_mov_b32 m0, s9
	v_lshl_add_u64 v[134:135], s[18:19], 0, v[144:145]
	global_load_lds_dwordx4 v[134:135], off
	v_lshl_add_u64 v[136:137], s[18:19], 0, v[146:147]
	s_mov_b32 m0, s36
	s_nop 0
	global_load_lds_dwordx4 v[136:137], off
	s_add_u32 s48, s14, 0x40000
	s_addc_u32 s49, s15, 0
	s_add_i32 s20, s35, s5
	v_lshl_add_u64 v[138:139], s[48:49], 0, v[128:129]
	s_mov_b32 m0, s20
	s_nop 0
	global_load_lds_dwordx4 v[138:139], off
	v_lshl_add_u64 v[138:139], s[48:49], 0, v[148:149]
	s_add_i32 m0, s20, 0x2000
	s_nop 0
	global_load_lds_dwordx4 v[138:139], off
	s_waitcnt vmcnt(8) lgkmcnt(0)
	s_barrier
	v_mfma_f32_16x16x32_bf16 v[60:63], v[154:157], v[176:179], v[60:63]
	v_mfma_f32_16x16x32_bf16 v[56:59], v[168:171], v[176:179], v[56:59]
	v_mfma_f32_16x16x32_bf16 v[44:47], v[154:157], v[184:187], v[44:47]
	v_mfma_f32_16x16x32_bf16 v[40:43], v[168:171], v[184:187], v[40:43]
	v_mfma_f32_16x16x32_bf16 v[28:31], v[154:157], v[192:195], v[28:31]
	v_mfma_f32_16x16x32_bf16 v[24:27], v[168:171], v[192:195], v[24:27]
	v_mfma_f32_16x16x32_bf16 v[12:15], v[154:157], v[200:203], v[12:15]
	v_mfma_f32_16x16x32_bf16 v[8:11], v[168:171], v[200:203], v[8:11]
	v_mfma_f32_16x16x32_bf16 v[60:63], v[164:167], v[180:183], v[60:63]
	v_mfma_f32_16x16x32_bf16 v[56:59], v[172:175], v[180:183], v[56:59]
	v_mfma_f32_16x16x32_bf16 v[44:47], v[164:167], v[188:191], v[44:47]
	v_mfma_f32_16x16x32_bf16 v[40:43], v[172:175], v[188:191], v[40:43]
	v_mfma_f32_16x16x32_bf16 v[28:31], v[164:167], v[196:199], v[28:31]
	v_mfma_f32_16x16x32_bf16 v[24:27], v[172:175], v[196:199], v[24:27]
	v_mfma_f32_16x16x32_bf16 v[12:15], v[164:167], v[204:207], v[12:15]
	v_mfma_f32_16x16x32_bf16 v[8:11], v[172:175], v[204:207], v[8:11]
	v_mfma_f32_16x16x32_bf16 v[52:55], v[208:211], v[176:179], v[52:55]
	v_mfma_f32_16x16x32_bf16 v[48:51], v[216:219], v[176:179], v[48:51]
	v_mfma_f32_16x16x32_bf16 v[36:39], v[208:211], v[184:187], v[36:39]
	v_mfma_f32_16x16x32_bf16 v[32:35], v[216:219], v[184:187], v[32:35]
	v_mfma_f32_16x16x32_bf16 v[20:23], v[208:211], v[192:195], v[20:23]
	v_mfma_f32_16x16x32_bf16 v[16:19], v[216:219], v[192:195], v[16:19]
	v_mfma_f32_16x16x32_bf16 v[4:7], v[208:211], v[200:203], v[4:7]
	v_mfma_f32_16x16x32_bf16 v[0:3], v[216:219], v[200:203], v[0:3]
	v_mfma_f32_16x16x32_bf16 v[52:55], v[212:215], v[180:183], v[52:55]
	v_mfma_f32_16x16x32_bf16 v[48:51], v[220:223], v[180:183], v[48:51]
	v_mfma_f32_16x16x32_bf16 v[36:39], v[212:215], v[188:191], v[36:39]
	v_mfma_f32_16x16x32_bf16 v[32:35], v[220:223], v[188:191], v[32:35]
	v_mfma_f32_16x16x32_bf16 v[20:23], v[212:215], v[196:199], v[20:23]
	v_mfma_f32_16x16x32_bf16 v[16:19], v[220:223], v[196:199], v[16:19]
	v_mfma_f32_16x16x32_bf16 v[4:7], v[212:215], v[204:207], v[4:7]
	v_mfma_f32_16x16x32_bf16 v[0:3], v[220:223], v[204:207], v[0:3]
	s_add_i32 s20, 16, 0x18000
	v_add_u32_e32 v138, s20, v160
	s_barrier
	ds_read_b128 v[154:157], v138
	ds_read_b128 v[164:167], v138 offset:1024
	ds_read_b128 v[168:171], v138 offset:2048
	ds_read_b128 v[172:175], v138 offset:3072
	s_add_u32 s18, s18, 0x40000
	s_addc_u32 s19, s19, 0
	s_mov_b32 m0, s37
	v_lshl_add_u64 v[158:159], s[18:19], 0, v[144:145]
	ds_read_b128 v[176:179], v162 offset:32768
	ds_read_b128 v[180:183], v162 offset:33792
	ds_read_b128 v[184:187], v162 offset:34816
	ds_read_b128 v[188:191], v162 offset:35840
	ds_read_b128 v[192:195], v162 offset:36864
	ds_read_b128 v[196:199], v162 offset:37888
	ds_read_b128 v[200:203], v162 offset:38912
	ds_read_b128 v[204:207], v162 offset:39936
	global_load_lds_dwordx4 v[158:159], off
	v_lshl_add_u64 v[158:159], s[18:19], 0, v[146:147]
	s_mov_b32 m0, s46
	s_nop 0
	global_load_lds_dwordx4 v[158:159], off
	s_add_i32 s18, 16, 0x1c000
	v_add_u32_e32 v138, s18, v160
	ds_read_b128 v[208:211], v138
	ds_read_b128 v[212:215], v138 offset:1024
	ds_read_b128 v[216:219], v138 offset:2048
	ds_read_b128 v[220:223], v138 offset:3072
	s_waitcnt vmcnt(8) lgkmcnt(0)
	s_barrier
	v_mfma_f32_16x16x32_bf16 v[124:127], v[154:157], v[176:179], v[124:127]
	v_mfma_f32_16x16x32_bf16 v[120:123], v[168:171], v[176:179], v[120:123]
	v_mfma_f32_16x16x32_bf16 v[108:111], v[154:157], v[184:187], v[108:111]
	v_mfma_f32_16x16x32_bf16 v[104:107], v[168:171], v[184:187], v[104:107]
	v_mfma_f32_16x16x32_bf16 v[92:95], v[154:157], v[192:195], v[92:95]
	v_mfma_f32_16x16x32_bf16 v[88:91], v[168:171], v[192:195], v[88:91]
	v_mfma_f32_16x16x32_bf16 v[76:79], v[154:157], v[200:203], v[76:79]
	v_mfma_f32_16x16x32_bf16 v[72:75], v[168:171], v[200:203], v[72:75]
	v_mfma_f32_16x16x32_bf16 v[124:127], v[164:167], v[180:183], v[124:127]
	v_mfma_f32_16x16x32_bf16 v[120:123], v[172:175], v[180:183], v[120:123]
	v_mfma_f32_16x16x32_bf16 v[108:111], v[164:167], v[188:191], v[108:111]
	v_mfma_f32_16x16x32_bf16 v[104:107], v[172:175], v[188:191], v[104:107]
	v_mfma_f32_16x16x32_bf16 v[92:95], v[164:167], v[196:199], v[92:95]
	v_mfma_f32_16x16x32_bf16 v[88:91], v[172:175], v[196:199], v[88:91]
	v_mfma_f32_16x16x32_bf16 v[76:79], v[164:167], v[204:207], v[76:79]
	v_mfma_f32_16x16x32_bf16 v[72:75], v[172:175], v[204:207], v[72:75]
	v_mfma_f32_16x16x32_bf16 v[116:119], v[208:211], v[176:179], v[116:119]
	v_mfma_f32_16x16x32_bf16 v[112:115], v[216:219], v[176:179], v[112:115]
	v_mfma_f32_16x16x32_bf16 v[100:103], v[208:211], v[184:187], v[100:103]
	v_mfma_f32_16x16x32_bf16 v[96:99], v[216:219], v[184:187], v[96:99]
	v_mfma_f32_16x16x32_bf16 v[84:87], v[208:211], v[192:195], v[84:87]
	v_mfma_f32_16x16x32_bf16 v[80:83], v[216:219], v[192:195], v[80:83]
	v_mfma_f32_16x16x32_bf16 v[68:71], v[208:211], v[200:203], v[68:71]
	v_mfma_f32_16x16x32_bf16 v[64:67], v[216:219], v[200:203], v[64:67]
	v_mfma_f32_16x16x32_bf16 v[116:119], v[212:215], v[180:183], v[116:119]
	v_mfma_f32_16x16x32_bf16 v[112:115], v[220:223], v[180:183], v[112:115]
	v_mfma_f32_16x16x32_bf16 v[100:103], v[212:215], v[188:191], v[100:103]
	v_mfma_f32_16x16x32_bf16 v[96:99], v[220:223], v[188:191], v[96:99]
	v_mfma_f32_16x16x32_bf16 v[84:87], v[212:215], v[196:199], v[84:87]
	v_mfma_f32_16x16x32_bf16 v[80:83], v[220:223], v[196:199], v[80:83]
	v_mfma_f32_16x16x32_bf16 v[68:71], v[212:215], v[204:207], v[68:71]
	v_mfma_f32_16x16x32_bf16 v[64:67], v[220:223], v[204:207], v[64:67]
	s_barrier
	ds_read_b128 v[176:179], v162 offset:49152
	ds_read_b128 v[180:183], v162 offset:50176
	ds_read_b128 v[184:187], v162 offset:51200
	ds_read_b128 v[188:191], v162 offset:52224
	ds_read_b128 v[192:195], v162 offset:53248
	ds_read_b128 v[196:199], v162 offset:54272
	ds_read_b128 v[200:203], v162 offset:55296
	ds_read_b128 v[204:207], v162 offset:56320
	s_add_i32 s19, s20, s5
	v_lshl_add_u64 v[130:131], v[130:131], 0, s[28:29]
	s_mov_b32 m0, s19
	s_nop 0
	global_load_lds_dwordx4 v[130:131], off
	v_lshl_add_u64 v[130:131], v[132:133], 0, s[28:29]
	s_add_i32 m0, s19, 0x2000
	s_nop 0
	global_load_lds_dwordx4 v[130:131], off
	s_mov_b32 m0, s47
	v_lshl_add_u64 v[130:131], v[134:135], 0, s[28:29]
	global_load_lds_dwordx4 v[130:131], off
	v_lshl_add_u64 v[130:131], v[136:137], 0, s[28:29]
	s_mov_b32 m0, s92
	s_nop 0
	global_load_lds_dwordx4 v[130:131], off
	s_add_u32 s14, s14, 0x40080
	s_addc_u32 s15, s15, 0
	s_add_i32 s18, s18, s5
	v_lshl_add_u64 v[130:131], s[14:15], 0, v[128:129]
	s_mov_b32 m0, s18
	s_nop 0
	global_load_lds_dwordx4 v[130:131], off
	v_lshl_add_u64 v[130:131], s[14:15], 0, v[148:149]
	s_add_i32 m0, s18, 0x2000
	s_nop 0
	global_load_lds_dwordx4 v[130:131], off
	s_waitcnt vmcnt(8) lgkmcnt(0)
	s_barrier
	v_mfma_f32_16x16x32_bf16 v[60:63], v[154:157], v[176:179], v[60:63]
	v_mfma_f32_16x16x32_bf16 v[56:59], v[168:171], v[176:179], v[56:59]
	v_mfma_f32_16x16x32_bf16 v[44:47], v[154:157], v[184:187], v[44:47]
	v_mfma_f32_16x16x32_bf16 v[40:43], v[168:171], v[184:187], v[40:43]
	v_mfma_f32_16x16x32_bf16 v[28:31], v[154:157], v[192:195], v[28:31]
	v_mfma_f32_16x16x32_bf16 v[24:27], v[168:171], v[192:195], v[24:27]
	v_mfma_f32_16x16x32_bf16 v[12:15], v[154:157], v[200:203], v[12:15]
	v_mfma_f32_16x16x32_bf16 v[8:11], v[168:171], v[200:203], v[8:11]
	v_mfma_f32_16x16x32_bf16 v[60:63], v[164:167], v[180:183], v[60:63]
	v_mfma_f32_16x16x32_bf16 v[56:59], v[172:175], v[180:183], v[56:59]
	v_mfma_f32_16x16x32_bf16 v[44:47], v[164:167], v[188:191], v[44:47]
	v_mfma_f32_16x16x32_bf16 v[40:43], v[172:175], v[188:191], v[40:43]
	v_mfma_f32_16x16x32_bf16 v[28:31], v[164:167], v[196:199], v[28:31]
	v_mfma_f32_16x16x32_bf16 v[24:27], v[172:175], v[196:199], v[24:27]
	v_mfma_f32_16x16x32_bf16 v[12:15], v[164:167], v[204:207], v[12:15]
	v_mfma_f32_16x16x32_bf16 v[8:11], v[172:175], v[204:207], v[8:11]
	v_mfma_f32_16x16x32_bf16 v[52:55], v[208:211], v[176:179], v[52:55]
	v_mfma_f32_16x16x32_bf16 v[48:51], v[216:219], v[176:179], v[48:51]
	v_mfma_f32_16x16x32_bf16 v[36:39], v[208:211], v[184:187], v[36:39]
	v_mfma_f32_16x16x32_bf16 v[32:35], v[216:219], v[184:187], v[32:35]
	v_mfma_f32_16x16x32_bf16 v[20:23], v[208:211], v[192:195], v[20:23]
	v_mfma_f32_16x16x32_bf16 v[16:19], v[216:219], v[192:195], v[16:19]
	v_mfma_f32_16x16x32_bf16 v[4:7], v[208:211], v[200:203], v[4:7]
	v_mfma_f32_16x16x32_bf16 v[0:3], v[216:219], v[200:203], v[0:3]
	v_mfma_f32_16x16x32_bf16 v[52:55], v[212:215], v[180:183], v[52:55]
	v_mfma_f32_16x16x32_bf16 v[48:51], v[220:223], v[180:183], v[48:51]
	v_mfma_f32_16x16x32_bf16 v[36:39], v[212:215], v[188:191], v[36:39]
	v_mfma_f32_16x16x32_bf16 v[32:35], v[220:223], v[188:191], v[32:35]
	v_mfma_f32_16x16x32_bf16 v[20:23], v[212:215], v[196:199], v[20:23]
	v_mfma_f32_16x16x32_bf16 v[16:19], v[220:223], v[196:199], v[16:19]
	v_mfma_f32_16x16x32_bf16 v[4:7], v[212:215], v[204:207], v[4:7]
	v_mfma_f32_16x16x32_bf16 v[0:3], v[220:223], v[204:207], v[0:3]
	s_add_i32 s34, s34, 2
	s_add_u32 vcc_lo, vcc_lo, 0x100
	s_addc_u32 vcc_hi, vcc_hi, 0
	s_add_u32 s25, s25, 0x100
	s_addc_u32 s31, s31, 0
	s_cmp_gt_u32 s34, 13
	s_cbranch_scc1 .Lgout_exit
	s_branch .Lgout_head

.Lgout_epi:
	s_setprio 0
	s_nop 0
	s_nop 0
	s_nop 0
	s_nop 0
	s_nop 0
	s_nop 0
	s_nop 0
	s_cmp_lt_i32 s8, 0
	s_cselect_b64 s[14:15], -1, 0
	s_cmp_gt_i32 s8, -1
	s_cbranch_scc1 .LBB0_131
	v_mul_f32_e32 v131, 0x3d372713, v120
	v_mul_f32_e32 v131, v120, v131
	v_fma_f32 v131, v120, v131, v120
	v_mul_f32_e32 v131, 0x3fcc422a, v131
	v_mul_f32_e32 v131, 0xbfb8aa3b, v131
	v_exp_f32_e32 v131, v131
	v_mul_f32_e32 v130, 0x3d372713, v124
	v_mul_f32_e32 v130, v124, v130
	v_fma_f32 v130, v124, v130, v124
	v_add_f32_e32 v131, 1.0, v131
	v_rcp_f32_e32 v132, v131
	v_mul_f32_e32 v131, 0x3d372713, v125
	v_mul_f32_e32 v131, v125, v131
	v_fma_f32 v131, v125, v131, v125
	v_mul_f32_e32 v130, 0x3fcc422a, v130
	v_mul_f32_e32 v131, 0x3fcc422a, v131
	v_mul_f32_e32 v130, 0xbfb8aa3b, v130
	v_mul_f32_e32 v131, 0xbfb8aa3b, v131
	v_mul_f32_e32 v135, 0x3d372713, v122
	v_exp_f32_e32 v130, v130
	v_exp_f32_e32 v131, v131
	v_mul_f32_e32 v135, v122, v135
	v_fma_f32 v135, v122, v135, v122
	v_mul_f32_e32 v135, 0x3fcc422a, v135
	v_mul_f32_e32 v135, 0xbfb8aa3b, v135
	v_add_f32_e32 v130, 1.0, v130
	v_add_f32_e32 v131, 1.0, v131
	v_exp_f32_e32 v135, v135
	v_rcp_f32_e32 v130, v130
	v_rcp_f32_e32 v131, v131
	v_mul_f32_e32 v133, 0x3d372713, v121
	v_add_f32_e32 v135, 1.0, v135
	v_mul_f32_e32 v134, 0x3d372713, v126
	v_rcp_f32_e32 v136, v135
	v_mul_f32_e32 v135, 0x3d372713, v127
	v_pk_mul_f32 v[124:125], v[124:125], v[130:131]
	v_mul_f32_e32 v130, 0x3d372713, v123
	v_mul_f32_e32 v133, v121, v133
	v_mul_f32_e32 v134, v126, v134
	v_mul_f32_e32 v135, v127, v135
	v_mul_f32_e32 v130, v123, v130
	v_fma_f32 v133, v121, v133, v121
	v_fma_f32 v134, v126, v134, v126
	v_fma_f32 v135, v127, v135, v127
	v_fma_f32 v130, v123, v130, v123
	v_mul_f32_e32 v133, 0x3fcc422a, v133
	v_mul_f32_e32 v134, 0x3fcc422a, v134
	v_mul_f32_e32 v135, 0x3fcc422a, v135
	v_mul_f32_e32 v130, 0x3fcc422a, v130
	v_mul_f32_e32 v133, 0xbfb8aa3b, v133
	v_mul_f32_e32 v134, 0xbfb8aa3b, v134
	v_mul_f32_e32 v135, 0xbfb8aa3b, v135
	v_mul_f32_e32 v130, 0xbfb8aa3b, v130
	v_exp_f32_e32 v133, v133
	v_exp_f32_e32 v134, v134
	v_exp_f32_e32 v135, v135
	v_exp_f32_e32 v130, v130
	v_add_f32_e32 v133, 1.0, v133
	v_add_f32_e32 v134, 1.0, v134
	v_add_f32_e32 v135, 1.0, v135
	v_add_f32_e32 v130, 1.0, v130
	v_rcp_f32_e32 v133, v133
	v_rcp_f32_e32 v134, v134
	v_rcp_f32_e32 v135, v135
	v_rcp_f32_e32 v137, v130
	v_pk_mul_f32 v[120:121], v[120:121], v[132:133]
	v_pk_mul_f32 v[126:127], v[126:127], v[134:135]
	v_pk_mul_f32 v[122:123], v[122:123], v[136:137]

.LBB0_270:
	v_lshl_add_u32 v154, s14, 8, v143
	v_readlane_b32 s14, v252, 43
	v_mov_b64_e32 v[0:1], 0x600
	v_ashrrev_i32_e32 v155, 31, v154
	v_readlane_b32 s15, v252, 44
	v_cmp_lt_i64_e32 vcc, s[34:35], v[0:1]
	s_ashr_i32 s13, s12, 31
	v_lshl_add_u64 v[0:1], v[154:155], 2, s[14:15]
	global_load_dword v156, v[0:1], off
	global_load_dword v171, v[0:1], off offset:64
	global_load_dword v170, v[0:1], off offset:128
	global_load_dword v169, v[0:1], off offset:192
	global_load_dword v168, v[0:1], off offset:512
	global_load_dword v167, v[0:1], off offset:576
	global_load_dword v166, v[0:1], off offset:640
	global_load_dword v165, v[0:1], off offset:704
	s_lshl_b64 s[0:1], s[12:13], 19
	v_readlane_b32 s24, v252, 55
	v_readlane_b32 s25, v252, 56
	s_add_u32 s42, s24, s0
	s_addc_u32 s43, s25, s1
	s_and_b64 s[0:1], vcc, exec
	s_cselect_b32 s0, s43, s31
	s_cselect_b32 s1, s42, s30
	s_ashr_i32 s9, s8, 31
	s_lshl_b64 s[24:25], s[8:9], 19
	v_readlane_b32 s34, v252, 41
	v_readlane_b32 s35, v252, 42
	s_add_u32 s44, s34, s24
	s_addc_u32 s45, s35, s25
	s_and_b64 s[24:25], vcc, exec
	s_cselect_b32 s9, s45, s19
	s_cselect_b32 s13, s44, s18
	s_add_u32 s30, s30, 0x40080
	s_addc_u32 s31, s31, 0
	s_add_u32 s17, s18, 0x100
	v_mov_b32_e32 v0, 0
	s_addc_u32 s24, s19, 0
	s_mov_b32 s25, -2
	v_mov_b32_e32 v1, v0
	v_mov_b32_e32 v2, v0
	v_mov_b32_e32 v3, v0
	v_mov_b32_e32 v4, v0
	v_mov_b32_e32 v5, v0
	v_mov_b32_e32 v6, v0
	v_mov_b32_e32 v7, v0
	v_mov_b32_e32 v16, v0
	v_mov_b32_e32 v17, v0
	v_mov_b32_e32 v18, v0
	v_mov_b32_e32 v19, v0
	v_mov_b32_e32 v20, v0
	v_mov_b32_e32 v21, v0
	v_mov_b32_e32 v22, v0
	v_mov_b32_e32 v23, v0
	v_mov_b32_e32 v32, v0
	v_mov_b32_e32 v33, v0
	v_mov_b32_e32 v34, v0
	v_mov_b32_e32 v35, v0
	v_mov_b32_e32 v36, v0
	v_mov_b32_e32 v37, v0
	v_mov_b32_e32 v38, v0
	v_mov_b32_e32 v39, v0
	v_mov_b32_e32 v48, v0
	v_mov_b32_e32 v49, v0
	v_mov_b32_e32 v50, v0
	v_mov_b32_e32 v51, v0
	v_mov_b32_e32 v52, v0
	v_mov_b32_e32 v53, v0
	v_mov_b32_e32 v54, v0
	v_mov_b32_e32 v55, v0
	v_mov_b32_e32 v8, v0
	v_mov_b32_e32 v9, v0
	v_mov_b32_e32 v10, v0
	v_mov_b32_e32 v11, v0
	v_mov_b32_e32 v12, v0
	v_mov_b32_e32 v13, v0
	v_mov_b32_e32 v14, v0
	v_mov_b32_e32 v15, v0
	v_mov_b32_e32 v24, v0
	v_mov_b32_e32 v25, v0
	v_mov_b32_e32 v26, v0
	v_mov_b32_e32 v27, v0
	v_mov_b32_e32 v28, v0
	v_mov_b32_e32 v29, v0
	v_mov_b32_e32 v30, v0
	v_mov_b32_e32 v31, v0
	v_mov_b32_e32 v40, v0
	v_mov_b32_e32 v41, v0
	v_mov_b32_e32 v42, v0
	v_mov_b32_e32 v43, v0
	v_mov_b32_e32 v44, v0
	v_mov_b32_e32 v45, v0
	v_mov_b32_e32 v46, v0
	v_mov_b32_e32 v47, v0
	v_mov_b32_e32 v56, v0
	v_mov_b32_e32 v57, v0
	v_mov_b32_e32 v58, v0
	v_mov_b32_e32 v59, v0
	v_mov_b32_e32 v60, v0
	v_mov_b32_e32 v61, v0
	v_mov_b32_e32 v62, v0
	v_mov_b32_e32 v63, v0
	v_mov_b32_e32 v64, v0
	v_mov_b32_e32 v65, v0
	v_mov_b32_e32 v66, v0
	v_mov_b32_e32 v67, v0
	v_mov_b32_e32 v68, v0
	v_mov_b32_e32 v69, v0
	v_mov_b32_e32 v70, v0
	v_mov_b32_e32 v71, v0
	v_mov_b32_e32 v80, v0
	v_mov_b32_e32 v81, v0
	v_mov_b32_e32 v82, v0
	v_mov_b32_e32 v83, v0
	v_mov_b32_e32 v84, v0
	v_mov_b32_e32 v85, v0
	v_mov_b32_e32 v86, v0
	v_mov_b32_e32 v87, v0
	v_mov_b32_e32 v96, v0
	v_mov_b32_e32 v97, v0
	v_mov_b32_e32 v98, v0
	v_mov_b32_e32 v99, v0
	v_mov_b32_e32 v100, v0
	v_mov_b32_e32 v101, v0
	v_mov_b32_e32 v102, v0
	v_mov_b32_e32 v103, v0
	v_mov_b32_e32 v112, v0
	v_mov_b32_e32 v113, v0
	v_mov_b32_e32 v114, v0
	v_mov_b32_e32 v115, v0
	v_mov_b32_e32 v116, v0
	v_mov_b32_e32 v117, v0
	v_mov_b32_e32 v118, v0
	v_mov_b32_e32 v119, v0
	v_mov_b32_e32 v72, v0
	v_mov_b32_e32 v73, v0
	v_mov_b32_e32 v74, v0
	v_mov_b32_e32 v75, v0
	v_mov_b32_e32 v76, v0
	v_mov_b32_e32 v77, v0
	v_mov_b32_e32 v78, v0
	v_mov_b32_e32 v79, v0
	v_mov_b32_e32 v88, v0
	v_mov_b32_e32 v89, v0
	v_mov_b32_e32 v90, v0
	v_mov_b32_e32 v91, v0
	v_mov_b32_e32 v92, v0
	v_mov_b32_e32 v93, v0
	v_mov_b32_e32 v94, v0
	v_mov_b32_e32 v95, v0
	v_mov_b32_e32 v104, v0
	v_mov_b32_e32 v105, v0
	v_mov_b32_e32 v106, v0
	v_mov_b32_e32 v107, v0
	v_mov_b32_e32 v108, v0
	v_mov_b32_e32 v109, v0
	v_mov_b32_e32 v110, v0
	v_mov_b32_e32 v111, v0
	v_mov_b32_e32 v120, v0
	v_mov_b32_e32 v121, v0
	v_mov_b32_e32 v122, v0
	v_mov_b32_e32 v123, v0
	v_mov_b32_e32 v124, v0
	v_mov_b32_e32 v125, v0
	v_mov_b32_e32 v126, v0
	v_mov_b32_e32 v127, v0
	s_cmpk_gt_u32 s48, 0xff
	s_cbranch_scc0 .Lgin_enter
	s_setprio 1

.Lgin_enter:
.LBB0_271:
	s_add_u32 s14, s30, 0xfffc0080
	s_addc_u32 s15, s31, -1
	s_add_i32 s20, 16, 0x10000
	v_add_u32_e32 v130, s20, v162
	ds_read_b128 v[158:161], v130
	ds_read_b128 v[172:175], v130 offset:1024
	ds_read_b128 v[176:179], v130 offset:2048
	ds_read_b128 v[180:183], v130 offset:3072
	s_cmp_eq_u32 s25, 12
	s_cselect_b32 s19, s0, s15
	s_cselect_b32 s18, s1, s14
	s_cselect_b32 s15, s9, s24
	s_cselect_b32 s14, s13, s17
	v_lshl_add_u64 v[130:131], s[30:31], 0, v[150:151]
	s_add_i32 m0, s5, 0xc000
	ds_read_b128 v[184:187], v164
	ds_read_b128 v[188:191], v164 offset:1024
	ds_read_b128 v[192:195], v164 offset:2048
	ds_read_b128 v[196:199], v164 offset:3072
	ds_read_b128 v[200:203], v164 offset:4096
	ds_read_b128 v[204:207], v164 offset:5120
	ds_read_b128 v[208:211], v164 offset:6144
	ds_read_b128 v[212:215], v164 offset:7168
	global_load_lds_dwordx4 v[130:131], off
	v_lshl_add_u64 v[130:131], s[30:31], 0, v[152:153]
	s_add_i32 m0, s5, 0xe000
	s_nop 0
	global_load_lds_dwordx4 v[130:131], off
	s_add_i32 s41, 16, 0x14000
	v_add_u32_e32 v130, s41, v162
	ds_read_b128 v[216:219], v130
	ds_read_b128 v[220:223], v130 offset:1024
	ds_read_b128 v[224:227], v130 offset:2048
	ds_read_b128 v[228:231], v130 offset:3072
	s_waitcnt vmcnt(8) lgkmcnt(0)
	s_barrier
	v_mfma_f32_16x16x32_bf16 v[124:127], v[158:161], v[184:187], v[124:127]
	v_mfma_f32_16x16x32_bf16 v[120:123], v[176:179], v[184:187], v[120:123]
	v_mfma_f32_16x16x32_bf16 v[108:111], v[158:161], v[192:195], v[108:111]
	v_mfma_f32_16x16x32_bf16 v[104:107], v[176:179], v[192:195], v[104:107]
	v_mfma_f32_16x16x32_bf16 v[92:95], v[158:161], v[200:203], v[92:95]
	v_mfma_f32_16x16x32_bf16 v[88:91], v[176:179], v[200:203], v[88:91]
	v_mfma_f32_16x16x32_bf16 v[76:79], v[158:161], v[208:211], v[76:79]
	v_mfma_f32_16x16x32_bf16 v[72:75], v[176:179], v[208:211], v[72:75]
	v_mfma_f32_16x16x32_bf16 v[124:127], v[172:175], v[188:191], v[124:127]
	v_mfma_f32_16x16x32_bf16 v[120:123], v[180:183], v[188:191], v[120:123]
	v_mfma_f32_16x16x32_bf16 v[108:111], v[172:175], v[196:199], v[108:111]
	v_mfma_f32_16x16x32_bf16 v[104:107], v[180:183], v[196:199], v[104:107]
	v_mfma_f32_16x16x32_bf16 v[92:95], v[172:175], v[204:207], v[92:95]
	v_mfma_f32_16x16x32_bf16 v[88:91], v[180:183], v[204:207], v[88:91]
	v_mfma_f32_16x16x32_bf16 v[76:79], v[172:175], v[212:215], v[76:79]
	v_mfma_f32_16x16x32_bf16 v[72:75], v[180:183], v[212:215], v[72:75]
	v_mfma_f32_16x16x32_bf16 v[116:119], v[216:219], v[184:187], v[116:119]
	v_mfma_f32_16x16x32_bf16 v[112:115], v[224:227], v[184:187], v[112:115]
	v_mfma_f32_16x16x32_bf16 v[100:103], v[216:219], v[192:195], v[100:103]
	v_mfma_f32_16x16x32_bf16 v[96:99], v[224:227], v[192:195], v[96:99]
	v_mfma_f32_16x16x32_bf16 v[84:87], v[216:219], v[200:203], v[84:87]
	v_mfma_f32_16x16x32_bf16 v[80:83], v[224:227], v[200:203], v[80:83]
	v_mfma_f32_16x16x32_bf16 v[68:71], v[216:219], v[208:211], v[68:71]
	v_mfma_f32_16x16x32_bf16 v[64:67], v[224:227], v[208:211], v[64:67]
	v_mfma_f32_16x16x32_bf16 v[116:119], v[220:223], v[188:191], v[116:119]
	v_mfma_f32_16x16x32_bf16 v[112:115], v[228:231], v[188:191], v[112:115]
	v_mfma_f32_16x16x32_bf16 v[100:103], v[220:223], v[196:199], v[100:103]
	v_mfma_f32_16x16x32_bf16 v[96:99], v[228:231], v[196:199], v[96:99]
	v_mfma_f32_16x16x32_bf16 v[84:87], v[220:223], v[204:207], v[84:87]
	v_mfma_f32_16x16x32_bf16 v[80:83], v[228:231], v[204:207], v[80:83]
	v_mfma_f32_16x16x32_bf16 v[68:71], v[220:223], v[212:215], v[68:71]
	v_mfma_f32_16x16x32_bf16 v[64:67], v[228:231], v[212:215], v[64:67]
	s_barrier
	ds_read_b128 v[184:187], v164 offset:16384
	ds_read_b128 v[188:191], v164 offset:17408
	ds_read_b128 v[192:195], v164 offset:18432
	ds_read_b128 v[196:199], v164 offset:19456
	ds_read_b128 v[200:203], v164 offset:20480
	ds_read_b128 v[204:207], v164 offset:21504
	ds_read_b128 v[208:211], v164 offset:22528
	ds_read_b128 v[212:215], v164 offset:23552
	s_add_i32 s20, s20, s92
	v_lshl_add_u64 v[130:131], s[14:15], 0, v[128:129]
	s_mov_b32 m0, s20
	v_lshl_add_u64 v[132:133], s[14:15], 0, v[148:149]
	global_load_lds_dwordx4 v[130:131], off
	s_add_i32 m0, s20, 0x2000
	s_nop 0
	global_load_lds_dwordx4 v[132:133], off
	s_mov_b32 m0, s5
	v_lshl_add_u64 v[134:135], s[18:19], 0, v[144:145]
	global_load_lds_dwordx4 v[134:135], off
	v_lshl_add_u64 v[136:137], s[18:19], 0, v[146:147]
	s_mov_b32 m0, s4
	s_nop 0
	global_load_lds_dwordx4 v[136:137], off
	s_add_u32 s34, s14, 0x40000
	s_addc_u32 s35, s15, 0
	s_add_i32 s20, s41, s92
	v_lshl_add_u64 v[138:139], s[34:35], 0, v[128:129]
	s_mov_b32 m0, s20
	s_nop 0
	global_load_lds_dwordx4 v[138:139], off
	v_lshl_add_u64 v[138:139], s[34:35], 0, v[148:149]
	s_add_i32 m0, s20, 0x2000
	s_nop 0
	global_load_lds_dwordx4 v[138:139], off
	s_waitcnt vmcnt(8) lgkmcnt(0)
	s_barrier
	v_mfma_f32_16x16x32_bf16 v[60:63], v[158:161], v[184:187], v[60:63]
	v_mfma_f32_16x16x32_bf16 v[56:59], v[176:179], v[184:187], v[56:59]
	v_mfma_f32_16x16x32_bf16 v[44:47], v[158:161], v[192:195], v[44:47]
	v_mfma_f32_16x16x32_bf16 v[40:43], v[176:179], v[192:195], v[40:43]
	v_mfma_f32_16x16x32_bf16 v[28:31], v[158:161], v[200:203], v[28:31]
	v_mfma_f32_16x16x32_bf16 v[24:27], v[176:179], v[200:203], v[24:27]
	v_mfma_f32_16x16x32_bf16 v[12:15], v[158:161], v[208:211], v[12:15]
	v_mfma_f32_16x16x32_bf16 v[8:11], v[176:179], v[208:211], v[8:11]
	v_mfma_f32_16x16x32_bf16 v[60:63], v[172:175], v[188:191], v[60:63]
	v_mfma_f32_16x16x32_bf16 v[56:59], v[180:183], v[188:191], v[56:59]
	v_mfma_f32_16x16x32_bf16 v[44:47], v[172:175], v[196:199], v[44:47]
	v_mfma_f32_16x16x32_bf16 v[40:43], v[180:183], v[196:199], v[40:43]
	v_mfma_f32_16x16x32_bf16 v[28:31], v[172:175], v[204:207], v[28:31]
	v_mfma_f32_16x16x32_bf16 v[24:27], v[180:183], v[204:207], v[24:27]
	v_mfma_f32_16x16x32_bf16 v[12:15], v[172:175], v[212:215], v[12:15]
	v_mfma_f32_16x16x32_bf16 v[8:11], v[180:183], v[212:215], v[8:11]
	v_mfma_f32_16x16x32_bf16 v[52:55], v[216:219], v[184:187], v[52:55]
	v_mfma_f32_16x16x32_bf16 v[48:51], v[224:227], v[184:187], v[48:51]
	v_mfma_f32_16x16x32_bf16 v[36:39], v[216:219], v[192:195], v[36:39]
	v_mfma_f32_16x16x32_bf16 v[32:35], v[224:227], v[192:195], v[32:35]
	v_mfma_f32_16x16x32_bf16 v[20:23], v[216:219], v[200:203], v[20:23]
	v_mfma_f32_16x16x32_bf16 v[16:19], v[224:227], v[200:203], v[16:19]
	v_mfma_f32_16x16x32_bf16 v[4:7], v[216:219], v[208:211], v[4:7]
	v_mfma_f32_16x16x32_bf16 v[0:3], v[224:227], v[208:211], v[0:3]
	v_mfma_f32_16x16x32_bf16 v[52:55], v[220:223], v[188:191], v[52:55]
	v_mfma_f32_16x16x32_bf16 v[48:51], v[228:231], v[188:191], v[48:51]
	v_mfma_f32_16x16x32_bf16 v[36:39], v[220:223], v[196:199], v[36:39]
	v_mfma_f32_16x16x32_bf16 v[32:35], v[228:231], v[196:199], v[32:35]
	v_mfma_f32_16x16x32_bf16 v[20:23], v[220:223], v[204:207], v[20:23]
	v_mfma_f32_16x16x32_bf16 v[16:19], v[228:231], v[204:207], v[16:19]
	v_mfma_f32_16x16x32_bf16 v[4:7], v[220:223], v[212:215], v[4:7]
	v_mfma_f32_16x16x32_bf16 v[0:3], v[228:231], v[212:215], v[0:3]
	s_add_i32 s20, 16, 0x18000
	v_add_u32_e32 v138, s20, v162
	s_barrier
	ds_read_b128 v[158:161], v138
	ds_read_b128 v[172:175], v138 offset:1024
	ds_read_b128 v[176:179], v138 offset:2048
	ds_read_b128 v[180:183], v138 offset:3072
	s_add_u32 s18, s18, 0x40000
	s_addc_u32 s19, s19, 0
	s_mov_b32 m0, s36
	v_lshl_add_u64 v[216:217], s[18:19], 0, v[144:145]
	ds_read_b128 v[184:187], v164 offset:32768
	ds_read_b128 v[188:191], v164 offset:33792
	ds_read_b128 v[192:195], v164 offset:34816
	ds_read_b128 v[196:199], v164 offset:35840
	ds_read_b128 v[200:203], v164 offset:36864
	ds_read_b128 v[204:207], v164 offset:37888
	ds_read_b128 v[208:211], v164 offset:38912
	ds_read_b128 v[212:215], v164 offset:39936
	global_load_lds_dwordx4 v[216:217], off
	v_lshl_add_u64 v[216:217], s[18:19], 0, v[146:147]
	s_mov_b32 m0, s37
	s_nop 0
	global_load_lds_dwordx4 v[216:217], off
	s_add_i32 s18, 16, 0x1c000
	v_add_u32_e32 v138, s18, v162
	ds_read_b128 v[216:219], v138
	ds_read_b128 v[220:223], v138 offset:1024
	ds_read_b128 v[224:227], v138 offset:2048
	ds_read_b128 v[228:231], v138 offset:3072
	s_waitcnt vmcnt(8) lgkmcnt(0)
	s_barrier
	v_mfma_f32_16x16x32_bf16 v[124:127], v[158:161], v[184:187], v[124:127]
	v_mfma_f32_16x16x32_bf16 v[120:123], v[176:179], v[184:187], v[120:123]
	v_mfma_f32_16x16x32_bf16 v[108:111], v[158:161], v[192:195], v[108:111]
	v_mfma_f32_16x16x32_bf16 v[104:107], v[176:179], v[192:195], v[104:107]
	v_mfma_f32_16x16x32_bf16 v[92:95], v[158:161], v[200:203], v[92:95]
	v_mfma_f32_16x16x32_bf16 v[88:91], v[176:179], v[200:203], v[88:91]
	v_mfma_f32_16x16x32_bf16 v[76:79], v[158:161], v[208:211], v[76:79]
	v_mfma_f32_16x16x32_bf16 v[72:75], v[176:179], v[208:211], v[72:75]
	v_mfma_f32_16x16x32_bf16 v[124:127], v[172:175], v[188:191], v[124:127]
	v_mfma_f32_16x16x32_bf16 v[120:123], v[180:183], v[188:191], v[120:123]
	v_mfma_f32_16x16x32_bf16 v[108:111], v[172:175], v[196:199], v[108:111]
	v_mfma_f32_16x16x32_bf16 v[104:107], v[180:183], v[196:199], v[104:107]
	v_mfma_f32_16x16x32_bf16 v[92:95], v[172:175], v[204:207], v[92:95]
	v_mfma_f32_16x16x32_bf16 v[88:91], v[180:183], v[204:207], v[88:91]
	v_mfma_f32_16x16x32_bf16 v[76:79], v[172:175], v[212:215], v[76:79]
	v_mfma_f32_16x16x32_bf16 v[72:75], v[180:183], v[212:215], v[72:75]
	v_mfma_f32_16x16x32_bf16 v[116:119], v[216:219], v[184:187], v[116:119]
	v_mfma_f32_16x16x32_bf16 v[112:115], v[224:227], v[184:187], v[112:115]
	v_mfma_f32_16x16x32_bf16 v[100:103], v[216:219], v[192:195], v[100:103]
	v_mfma_f32_16x16x32_bf16 v[96:99], v[224:227], v[192:195], v[96:99]
	v_mfma_f32_16x16x32_bf16 v[84:87], v[216:219], v[200:203], v[84:87]
	v_mfma_f32_16x16x32_bf16 v[80:83], v[224:227], v[200:203], v[80:83]
	v_mfma_f32_16x16x32_bf16 v[68:71], v[216:219], v[208:211], v[68:71]
	v_mfma_f32_16x16x32_bf16 v[64:67], v[224:227], v[208:211], v[64:67]
	v_mfma_f32_16x16x32_bf16 v[116:119], v[220:223], v[188:191], v[116:119]
	v_mfma_f32_16x16x32_bf16 v[112:115], v[228:231], v[188:191], v[112:115]
	v_mfma_f32_16x16x32_bf16 v[100:103], v[220:223], v[196:199], v[100:103]
	v_mfma_f32_16x16x32_bf16 v[96:99], v[228:231], v[196:199], v[96:99]
	v_mfma_f32_16x16x32_bf16 v[84:87], v[220:223], v[204:207], v[84:87]
	v_mfma_f32_16x16x32_bf16 v[80:83], v[228:231], v[204:207], v[80:83]
	v_mfma_f32_16x16x32_bf16 v[68:71], v[220:223], v[212:215], v[68:71]
	v_mfma_f32_16x16x32_bf16 v[64:67], v[228:231], v[212:215], v[64:67]
	s_barrier
	ds_read_b128 v[184:187], v164 offset:49152
	ds_read_b128 v[188:191], v164 offset:50176
	ds_read_b128 v[192:195], v164 offset:51200
	ds_read_b128 v[196:199], v164 offset:52224
	ds_read_b128 v[200:203], v164 offset:53248
	ds_read_b128 v[204:207], v164 offset:54272
	ds_read_b128 v[208:211], v164 offset:55296
	ds_read_b128 v[212:215], v164 offset:56320
	s_add_i32 s19, s20, s92
	v_lshl_add_u64 v[130:131], v[130:131], 0, s[28:29]
	s_mov_b32 m0, s19
	s_nop 0
	global_load_lds_dwordx4 v[130:131], off
	v_lshl_add_u64 v[130:131], v[132:133], 0, s[28:29]
	s_add_i32 m0, s19, 0x2000
	s_nop 0
	global_load_lds_dwordx4 v[130:131], off
	s_mov_b32 m0, s46
	v_lshl_add_u64 v[130:131], v[134:135], 0, s[28:29]
	global_load_lds_dwordx4 v[130:131], off
	v_lshl_add_u64 v[130:131], v[136:137], 0, s[28:29]
	s_mov_b32 m0, s47
	s_nop 0
	global_load_lds_dwordx4 v[130:131], off
	s_add_u32 s14, s14, 0x40080
	s_addc_u32 s15, s15, 0
	s_add_i32 s18, s18, s92
	v_lshl_add_u64 v[130:131], s[14:15], 0, v[128:129]
	s_mov_b32 m0, s18
	s_nop 0
	global_load_lds_dwordx4 v[130:131], off
	v_lshl_add_u64 v[130:131], s[14:15], 0, v[148:149]
	s_add_i32 m0, s18, 0x2000
	s_nop 0
	global_load_lds_dwordx4 v[130:131], off
	s_waitcnt vmcnt(8) lgkmcnt(0)
	s_barrier
	v_mfma_f32_16x16x32_bf16 v[60:63], v[158:161], v[184:187], v[60:63]
	v_mfma_f32_16x16x32_bf16 v[56:59], v[176:179], v[184:187], v[56:59]
	v_mfma_f32_16x16x32_bf16 v[44:47], v[158:161], v[192:195], v[44:47]
	v_mfma_f32_16x16x32_bf16 v[40:43], v[176:179], v[192:195], v[40:43]
	v_mfma_f32_16x16x32_bf16 v[28:31], v[158:161], v[200:203], v[28:31]
	v_mfma_f32_16x16x32_bf16 v[24:27], v[176:179], v[200:203], v[24:27]
	v_mfma_f32_16x16x32_bf16 v[12:15], v[158:161], v[208:211], v[12:15]
	v_mfma_f32_16x16x32_bf16 v[8:11], v[176:179], v[208:211], v[8:11]
	v_mfma_f32_16x16x32_bf16 v[60:63], v[172:175], v[188:191], v[60:63]
	v_mfma_f32_16x16x32_bf16 v[56:59], v[180:183], v[188:191], v[56:59]
	v_mfma_f32_16x16x32_bf16 v[44:47], v[172:175], v[196:199], v[44:47]
	v_mfma_f32_16x16x32_bf16 v[40:43], v[180:183], v[196:199], v[40:43]
	v_mfma_f32_16x16x32_bf16 v[28:31], v[172:175], v[204:207], v[28:31]
	v_mfma_f32_16x16x32_bf16 v[24:27], v[180:183], v[204:207], v[24:27]
	v_mfma_f32_16x16x32_bf16 v[12:15], v[172:175], v[212:215], v[12:15]
	v_mfma_f32_16x16x32_bf16 v[8:11], v[180:183], v[212:215], v[8:11]
	v_mfma_f32_16x16x32_bf16 v[52:55], v[216:219], v[184:187], v[52:55]
	v_mfma_f32_16x16x32_bf16 v[48:51], v[224:227], v[184:187], v[48:51]
	v_mfma_f32_16x16x32_bf16 v[36:39], v[216:219], v[192:195], v[36:39]
	v_mfma_f32_16x16x32_bf16 v[32:35], v[224:227], v[192:195], v[32:35]
	v_mfma_f32_16x16x32_bf16 v[20:23], v[216:219], v[200:203], v[20:23]
	v_mfma_f32_16x16x32_bf16 v[16:19], v[224:227], v[200:203], v[16:19]
	v_mfma_f32_16x16x32_bf16 v[4:7], v[216:219], v[208:211], v[4:7]
	v_mfma_f32_16x16x32_bf16 v[0:3], v[224:227], v[208:211], v[0:3]
	v_mfma_f32_16x16x32_bf16 v[52:55], v[220:223], v[188:191], v[52:55]
	v_mfma_f32_16x16x32_bf16 v[48:51], v[228:231], v[188:191], v[48:51]
	v_mfma_f32_16x16x32_bf16 v[36:39], v[220:223], v[196:199], v[36:39]
	v_mfma_f32_16x16x32_bf16 v[32:35], v[228:231], v[196:199], v[32:35]
	v_mfma_f32_16x16x32_bf16 v[20:23], v[220:223], v[204:207], v[20:23]
	v_mfma_f32_16x16x32_bf16 v[16:19], v[228:231], v[204:207], v[16:19]
	v_mfma_f32_16x16x32_bf16 v[4:7], v[220:223], v[212:215], v[4:7]
	v_mfma_f32_16x16x32_bf16 v[0:3], v[228:231], v[212:215], v[0:3]
	s_add_i32 s25, s25, 2
	s_add_u32 s30, s30, 0x100
	s_addc_u32 s31, s31, 0
	s_add_u32 s17, s17, 0x100
	s_addc_u32 s24, s24, 0
	s_cmp_gt_u32 s25, 13
	s_cbranch_scc1 .Lgin_exit
	s_branch .Lgin_head

.Lgin_epi:
	s_setprio 0
	s_nop 0
	s_nop 0
	s_nop 0
	s_nop 0
	s_nop 0
	s_nop 0
	s_nop 0
	s_waitcnt vmcnt(8)
	v_fmamk_f32 v130, v156, 0x3a800000, v235
	v_mul_f32_e32 v131, 0x4b800000, v130
	v_cmp_gt_f32_e32 vcc, s86, v130
	s_cmp_lt_i32 s40, 4
	s_cselect_b64 s[14:15], -1, 0
	v_cndmask_b32_e32 v130, v130, v131, vcc
	v_rsq_f32_e32 v130, v130
	s_cmp_gt_i32 s40, 3
	v_mul_f32_e32 v131, 0x45800000, v130
	v_cndmask_b32_e32 v156, v130, v131, vcc
	v_pk_mul_f32 v[126:127], v[156:157], v[126:127] op_sel_hi:[0,1]
	v_pk_mul_f32 v[124:125], v[156:157], v[124:125] op_sel_hi:[0,1]
	v_pk_mul_f32 v[158:159], v[156:157], v[122:123] op_sel_hi:[0,1]
	v_pk_mul_f32 v[160:161], v[156:157], v[120:121] op_sel_hi:[0,1]
	s_cbranch_scc1 .LBB0_274
	v_mul_f32_e32 v121, 0x3d372713, v160
	v_mul_f32_e32 v121, v160, v121
	v_fma_f32 v121, v160, v121, v160
	v_mul_f32_e32 v121, 0x3fcc422a, v121
	v_mul_f32_e32 v121, 0xbfb8aa3b, v121
	v_exp_f32_e32 v121, v121
	v_mul_f32_e32 v120, 0x3d372713, v124
	v_mul_f32_e32 v120, v124, v120
	v_mov_b32_e32 v123, v125
	v_add_f32_e32 v121, 1.0, v121
	v_rcp_f32_e32 v122, v121
	v_mul_f32_e32 v121, 0x3d372713, v125
	v_mul_f32_e32 v121, v125, v121
	v_fma_f32 v120, v124, v120, v124
	v_fmac_f32_e32 v123, v123, v121
	v_mul_f32_e32 v120, 0x3fcc422a, v120
	v_mul_f32_e32 v121, 0x3fcc422a, v123
	v_mul_f32_e32 v120, 0xbfb8aa3b, v120
	v_mul_f32_e32 v121, 0xbfb8aa3b, v121
	v_mul_f32_e32 v131, 0x3d372713, v158
	v_exp_f32_e32 v120, v120
	v_exp_f32_e32 v121, v121
	v_mul_f32_e32 v131, v158, v131
	v_fma_f32 v131, v158, v131, v158
	v_mul_f32_e32 v131, 0x3fcc422a, v131
	v_mul_f32_e32 v131, 0xbfb8aa3b, v131
	v_add_f32_e32 v120, 1.0, v120
	v_add_f32_e32 v121, 1.0, v121
	v_exp_f32_e32 v131, v131
	v_rcp_f32_e32 v120, v120
	v_rcp_f32_e32 v121, v121
	v_mul_f32_e32 v123, 0x3d372713, v161
	v_mul_f32_e32 v123, v161, v123
	v_mov_b32_e32 v130, v161
	v_fmac_f32_e32 v130, v130, v123
	v_add_f32_e32 v131, 1.0, v131
	v_mul_f32_e32 v123, 0x3fcc422a, v130
	v_mul_f32_e32 v130, 0x3d372713, v126
	v_rcp_f32_e32 v132, v131
	v_mul_f32_e32 v131, 0x3d372713, v127
	v_pk_mul_f32 v[124:125], v[124:125], v[120:121]
	v_mul_f32_e32 v120, 0x3d372713, v159
	v_mul_f32_e32 v130, v126, v130
	v_mul_f32_e32 v131, v127, v131
	v_mul_f32_e32 v120, v159, v120
	v_fma_f32 v130, v126, v130, v126
	v_fma_f32 v131, v127, v131, v127
	v_fma_f32 v120, v159, v120, v159
	v_mul_f32_e32 v130, 0x3fcc422a, v130
	v_mul_f32_e32 v131, 0x3fcc422a, v131
	v_mul_f32_e32 v120, 0x3fcc422a, v120
	v_mul_f32_e32 v123, 0xbfb8aa3b, v123
	v_mul_f32_e32 v130, 0xbfb8aa3b, v130
	v_mul_f32_e32 v131, 0xbfb8aa3b, v131
	v_mul_f32_e32 v120, 0xbfb8aa3b, v120
	v_exp_f32_e32 v123, v123
	v_exp_f32_e32 v130, v130
	v_exp_f32_e32 v131, v131
	v_exp_f32_e32 v120, v120
	v_add_f32_e32 v123, 1.0, v123
	v_add_f32_e32 v130, 1.0, v130
	v_add_f32_e32 v131, 1.0, v131
	v_add_f32_e32 v120, 1.0, v120
	v_rcp_f32_e32 v123, v123
	v_rcp_f32_e32 v130, v130
	v_rcp_f32_e32 v131, v131
	v_rcp_f32_e32 v133, v120
	v_pk_mul_f32 v[160:161], v[160:161], v[122:123]
	v_pk_mul_f32 v[126:127], v[126:127], v[130:131]
	v_pk_mul_f32 v[158:159], v[158:159], v[132:133]

.LBB0_344:
	s_add_u32 s30, s18, 0xb0080
	s_addc_u32 s31, s19, 0
	s_add_u32 s0, s14, 0x100
	v_mov_b32_e32 v0, 0
	s_addc_u32 s1, s15, 0
	s_mov_b32 s25, -2
	v_mov_b32_e32 v1, v0
	v_mov_b32_e32 v2, v0
	v_mov_b32_e32 v3, v0
	v_mov_b32_e32 v4, v0
	v_mov_b32_e32 v5, v0
	v_mov_b32_e32 v6, v0
	v_mov_b32_e32 v7, v0
	v_mov_b32_e32 v16, v0
	v_mov_b32_e32 v17, v0
	v_mov_b32_e32 v18, v0
	v_mov_b32_e32 v19, v0
	v_mov_b32_e32 v20, v0
	v_mov_b32_e32 v21, v0
	v_mov_b32_e32 v22, v0
	v_mov_b32_e32 v23, v0
	v_mov_b32_e32 v32, v0
	v_mov_b32_e32 v33, v0
	v_mov_b32_e32 v34, v0
	v_mov_b32_e32 v35, v0
	v_mov_b32_e32 v36, v0
	v_mov_b32_e32 v37, v0
	v_mov_b32_e32 v38, v0
	v_mov_b32_e32 v39, v0
	v_mov_b32_e32 v48, v0
	v_mov_b32_e32 v49, v0
	v_mov_b32_e32 v50, v0
	v_mov_b32_e32 v51, v0
	v_mov_b32_e32 v52, v0
	v_mov_b32_e32 v53, v0
	v_mov_b32_e32 v54, v0
	v_mov_b32_e32 v55, v0
	v_mov_b32_e32 v8, v0
	v_mov_b32_e32 v9, v0
	v_mov_b32_e32 v10, v0
	v_mov_b32_e32 v11, v0
	v_mov_b32_e32 v12, v0
	v_mov_b32_e32 v13, v0
	v_mov_b32_e32 v14, v0
	v_mov_b32_e32 v15, v0
	v_mov_b32_e32 v24, v0
	v_mov_b32_e32 v25, v0
	v_mov_b32_e32 v26, v0
	v_mov_b32_e32 v27, v0
	v_mov_b32_e32 v28, v0
	v_mov_b32_e32 v29, v0
	v_mov_b32_e32 v30, v0
	v_mov_b32_e32 v31, v0
	v_mov_b32_e32 v40, v0
	v_mov_b32_e32 v41, v0
	v_mov_b32_e32 v42, v0
	v_mov_b32_e32 v43, v0
	v_mov_b32_e32 v44, v0
	v_mov_b32_e32 v45, v0
	v_mov_b32_e32 v46, v0
	v_mov_b32_e32 v47, v0
	v_mov_b32_e32 v56, v0
	v_mov_b32_e32 v57, v0
	v_mov_b32_e32 v58, v0
	v_mov_b32_e32 v59, v0
	v_mov_b32_e32 v60, v0
	v_mov_b32_e32 v61, v0
	v_mov_b32_e32 v62, v0
	v_mov_b32_e32 v63, v0
	v_mov_b32_e32 v64, v0
	v_mov_b32_e32 v65, v0
	v_mov_b32_e32 v66, v0
	v_mov_b32_e32 v67, v0
	v_mov_b32_e32 v68, v0
	v_mov_b32_e32 v69, v0
	v_mov_b32_e32 v70, v0
	v_mov_b32_e32 v71, v0
	v_mov_b32_e32 v80, v0
	v_mov_b32_e32 v81, v0
	v_mov_b32_e32 v82, v0
	v_mov_b32_e32 v83, v0
	v_mov_b32_e32 v84, v0
	v_mov_b32_e32 v85, v0
	v_mov_b32_e32 v86, v0
	v_mov_b32_e32 v87, v0
	v_mov_b32_e32 v96, v0
	v_mov_b32_e32 v97, v0
	v_mov_b32_e32 v98, v0
	v_mov_b32_e32 v99, v0
	v_mov_b32_e32 v100, v0
	v_mov_b32_e32 v101, v0
	v_mov_b32_e32 v102, v0
	v_mov_b32_e32 v103, v0
	v_mov_b32_e32 v112, v0
	v_mov_b32_e32 v113, v0
	v_mov_b32_e32 v114, v0
	v_mov_b32_e32 v115, v0
	v_mov_b32_e32 v116, v0
	v_mov_b32_e32 v117, v0
	v_mov_b32_e32 v118, v0
	v_mov_b32_e32 v119, v0
	v_mov_b32_e32 v72, v0
	v_mov_b32_e32 v73, v0
	v_mov_b32_e32 v74, v0
	v_mov_b32_e32 v75, v0
	v_mov_b32_e32 v76, v0
	v_mov_b32_e32 v77, v0
	v_mov_b32_e32 v78, v0
	v_mov_b32_e32 v79, v0
	v_mov_b32_e32 v88, v0
	v_mov_b32_e32 v89, v0
	v_mov_b32_e32 v90, v0
	v_mov_b32_e32 v91, v0
	v_mov_b32_e32 v92, v0
	v_mov_b32_e32 v93, v0
	v_mov_b32_e32 v94, v0
	v_mov_b32_e32 v95, v0
	v_mov_b32_e32 v104, v0
	v_mov_b32_e32 v105, v0
	v_mov_b32_e32 v106, v0
	v_mov_b32_e32 v107, v0
	v_mov_b32_e32 v108, v0
	v_mov_b32_e32 v109, v0
	v_mov_b32_e32 v110, v0
	v_mov_b32_e32 v111, v0
	v_mov_b32_e32 v120, v0
	v_mov_b32_e32 v121, v0
	v_mov_b32_e32 v122, v0
	v_mov_b32_e32 v123, v0
	v_mov_b32_e32 v124, v0
	v_mov_b32_e32 v125, v0
	v_mov_b32_e32 v126, v0
	v_mov_b32_e32 v127, v0
	s_cmpk_gt_u32 s48, 0xff
	s_cbranch_scc0 .Lg2_enter
	s_setprio 1

.Lg2_enter:
.LBB0_345:
	s_add_u32 s14, s30, 0xfff50080
	s_addc_u32 s15, s31, -1
	s_add_i32 s20, 16, 0x10000
	v_add_u32_e32 v130, s20, v160
	ds_read_b128 v[154:157], v130
	ds_read_b128 v[164:167], v130 offset:1024
	ds_read_b128 v[168:171], v130 offset:2048
	ds_read_b128 v[172:175], v130 offset:3072
	s_cmp_eq_u32 s25, 40
	s_cselect_b32 s19, s9, s15
	s_cselect_b32 s18, s8, s14
	s_cselect_b32 s15, s13, s1
	s_cselect_b32 s14, s12, s0
	v_lshl_add_u64 v[130:131], s[30:31], 0, v[150:151]
	s_add_i32 m0, s34, 0xc000
	ds_read_b128 v[176:179], v162
	ds_read_b128 v[180:183], v162 offset:1024
	ds_read_b128 v[184:187], v162 offset:2048
	ds_read_b128 v[188:191], v162 offset:3072
	ds_read_b128 v[192:195], v162 offset:4096
	ds_read_b128 v[196:199], v162 offset:5120
	ds_read_b128 v[200:203], v162 offset:6144
	ds_read_b128 v[204:207], v162 offset:7168
	global_load_lds_dwordx4 v[130:131], off
	v_lshl_add_u64 v[130:131], s[30:31], 0, v[152:153]
	s_add_i32 m0, s34, 0xe000
	s_nop 0
	global_load_lds_dwordx4 v[130:131], off
	s_add_i32 s42, 16, 0x14000
	v_add_u32_e32 v130, s42, v160
	ds_read_b128 v[208:211], v130
	ds_read_b128 v[212:215], v130 offset:1024
	ds_read_b128 v[216:219], v130 offset:2048
	ds_read_b128 v[220:223], v130 offset:3072
	s_waitcnt vmcnt(8) lgkmcnt(0)
	s_barrier
	v_mfma_f32_16x16x32_bf16 v[124:127], v[154:157], v[176:179], v[124:127]
	v_mfma_f32_16x16x32_bf16 v[120:123], v[168:171], v[176:179], v[120:123]
	v_mfma_f32_16x16x32_bf16 v[108:111], v[154:157], v[184:187], v[108:111]
	v_mfma_f32_16x16x32_bf16 v[104:107], v[168:171], v[184:187], v[104:107]
	v_mfma_f32_16x16x32_bf16 v[92:95], v[154:157], v[192:195], v[92:95]
	v_mfma_f32_16x16x32_bf16 v[88:91], v[168:171], v[192:195], v[88:91]
	v_mfma_f32_16x16x32_bf16 v[76:79], v[154:157], v[200:203], v[76:79]
	v_mfma_f32_16x16x32_bf16 v[72:75], v[168:171], v[200:203], v[72:75]
	v_mfma_f32_16x16x32_bf16 v[124:127], v[164:167], v[180:183], v[124:127]
	v_mfma_f32_16x16x32_bf16 v[120:123], v[172:175], v[180:183], v[120:123]
	v_mfma_f32_16x16x32_bf16 v[108:111], v[164:167], v[188:191], v[108:111]
	v_mfma_f32_16x16x32_bf16 v[104:107], v[172:175], v[188:191], v[104:107]
	v_mfma_f32_16x16x32_bf16 v[92:95], v[164:167], v[196:199], v[92:95]
	v_mfma_f32_16x16x32_bf16 v[88:91], v[172:175], v[196:199], v[88:91]
	v_mfma_f32_16x16x32_bf16 v[76:79], v[164:167], v[204:207], v[76:79]
	v_mfma_f32_16x16x32_bf16 v[72:75], v[172:175], v[204:207], v[72:75]
	v_mfma_f32_16x16x32_bf16 v[116:119], v[208:211], v[176:179], v[116:119]
	v_mfma_f32_16x16x32_bf16 v[112:115], v[216:219], v[176:179], v[112:115]
	v_mfma_f32_16x16x32_bf16 v[100:103], v[208:211], v[184:187], v[100:103]
	v_mfma_f32_16x16x32_bf16 v[96:99], v[216:219], v[184:187], v[96:99]
	v_mfma_f32_16x16x32_bf16 v[84:87], v[208:211], v[192:195], v[84:87]
	v_mfma_f32_16x16x32_bf16 v[80:83], v[216:219], v[192:195], v[80:83]
	v_mfma_f32_16x16x32_bf16 v[68:71], v[208:211], v[200:203], v[68:71]
	v_mfma_f32_16x16x32_bf16 v[64:67], v[216:219], v[200:203], v[64:67]
	v_mfma_f32_16x16x32_bf16 v[116:119], v[212:215], v[180:183], v[116:119]
	v_mfma_f32_16x16x32_bf16 v[112:115], v[220:223], v[180:183], v[112:115]
	v_mfma_f32_16x16x32_bf16 v[100:103], v[212:215], v[188:191], v[100:103]
	v_mfma_f32_16x16x32_bf16 v[96:99], v[220:223], v[188:191], v[96:99]
	v_mfma_f32_16x16x32_bf16 v[84:87], v[212:215], v[196:199], v[84:87]
	v_mfma_f32_16x16x32_bf16 v[80:83], v[220:223], v[196:199], v[80:83]
	v_mfma_f32_16x16x32_bf16 v[68:71], v[212:215], v[204:207], v[68:71]
	v_mfma_f32_16x16x32_bf16 v[64:67], v[220:223], v[204:207], v[64:67]
	s_barrier
	ds_read_b128 v[176:179], v162 offset:16384
	ds_read_b128 v[180:183], v162 offset:17408
	ds_read_b128 v[184:187], v162 offset:18432
	ds_read_b128 v[188:191], v162 offset:19456
	ds_read_b128 v[192:195], v162 offset:20480
	ds_read_b128 v[196:199], v162 offset:21504
	ds_read_b128 v[200:203], v162 offset:22528
	ds_read_b128 v[204:207], v162 offset:23552
	s_add_i32 s20, s20, s5
	v_lshl_add_u64 v[130:131], s[14:15], 0, v[128:129]
	s_mov_b32 m0, s20
	v_lshl_add_u64 v[132:133], s[14:15], 0, v[148:149]
	global_load_lds_dwordx4 v[130:131], off
	s_add_i32 m0, s20, 0x2000
	s_nop 0
	global_load_lds_dwordx4 v[132:133], off
	s_mov_b32 m0, s34
	v_lshl_add_u64 v[134:135], s[18:19], 0, v[144:145]
	global_load_lds_dwordx4 v[134:135], off
	v_lshl_add_u64 v[136:137], s[18:19], 0, v[146:147]
	s_mov_b32 m0, s35
	s_nop 0
	global_load_lds_dwordx4 v[136:137], off
	s_add_u32 s40, s14, 0xb0000
	s_addc_u32 s41, s15, 0
	s_add_i32 s20, s42, s5
	v_lshl_add_u64 v[138:139], s[40:41], 0, v[128:129]
	s_mov_b32 m0, s20
	s_nop 0
	global_load_lds_dwordx4 v[138:139], off
	v_lshl_add_u64 v[138:139], s[40:41], 0, v[148:149]
	s_add_i32 m0, s20, 0x2000
	s_nop 0
	global_load_lds_dwordx4 v[138:139], off
	s_waitcnt vmcnt(8) lgkmcnt(0)
	s_barrier
	v_mfma_f32_16x16x32_bf16 v[60:63], v[154:157], v[176:179], v[60:63]
	v_mfma_f32_16x16x32_bf16 v[56:59], v[168:171], v[176:179], v[56:59]
	v_mfma_f32_16x16x32_bf16 v[44:47], v[154:157], v[184:187], v[44:47]
	v_mfma_f32_16x16x32_bf16 v[40:43], v[168:171], v[184:187], v[40:43]
	v_mfma_f32_16x16x32_bf16 v[28:31], v[154:157], v[192:195], v[28:31]
	v_mfma_f32_16x16x32_bf16 v[24:27], v[168:171], v[192:195], v[24:27]
	v_mfma_f32_16x16x32_bf16 v[12:15], v[154:157], v[200:203], v[12:15]
	v_mfma_f32_16x16x32_bf16 v[8:11], v[168:171], v[200:203], v[8:11]
	v_mfma_f32_16x16x32_bf16 v[60:63], v[164:167], v[180:183], v[60:63]
	v_mfma_f32_16x16x32_bf16 v[56:59], v[172:175], v[180:183], v[56:59]
	v_mfma_f32_16x16x32_bf16 v[44:47], v[164:167], v[188:191], v[44:47]
	v_mfma_f32_16x16x32_bf16 v[40:43], v[172:175], v[188:191], v[40:43]
	v_mfma_f32_16x16x32_bf16 v[28:31], v[164:167], v[196:199], v[28:31]
	v_mfma_f32_16x16x32_bf16 v[24:27], v[172:175], v[196:199], v[24:27]
	v_mfma_f32_16x16x32_bf16 v[12:15], v[164:167], v[204:207], v[12:15]
	v_mfma_f32_16x16x32_bf16 v[8:11], v[172:175], v[204:207], v[8:11]
	v_mfma_f32_16x16x32_bf16 v[52:55], v[208:211], v[176:179], v[52:55]
	v_mfma_f32_16x16x32_bf16 v[48:51], v[216:219], v[176:179], v[48:51]
	v_mfma_f32_16x16x32_bf16 v[36:39], v[208:211], v[184:187], v[36:39]
	v_mfma_f32_16x16x32_bf16 v[32:35], v[216:219], v[184:187], v[32:35]
	v_mfma_f32_16x16x32_bf16 v[20:23], v[208:211], v[192:195], v[20:23]
	v_mfma_f32_16x16x32_bf16 v[16:19], v[216:219], v[192:195], v[16:19]
	v_mfma_f32_16x16x32_bf16 v[4:7], v[208:211], v[200:203], v[4:7]
	v_mfma_f32_16x16x32_bf16 v[0:3], v[216:219], v[200:203], v[0:3]
	v_mfma_f32_16x16x32_bf16 v[52:55], v[212:215], v[180:183], v[52:55]
	v_mfma_f32_16x16x32_bf16 v[48:51], v[220:223], v[180:183], v[48:51]
	v_mfma_f32_16x16x32_bf16 v[36:39], v[212:215], v[188:191], v[36:39]
	v_mfma_f32_16x16x32_bf16 v[32:35], v[220:223], v[188:191], v[32:35]
	v_mfma_f32_16x16x32_bf16 v[20:23], v[212:215], v[196:199], v[20:23]
	v_mfma_f32_16x16x32_bf16 v[16:19], v[220:223], v[196:199], v[16:19]
	v_mfma_f32_16x16x32_bf16 v[4:7], v[212:215], v[204:207], v[4:7]
	v_mfma_f32_16x16x32_bf16 v[0:3], v[220:223], v[204:207], v[0:3]
	s_add_i32 s20, 16, 0x18000
	v_add_u32_e32 v138, s20, v160
	s_barrier
	ds_read_b128 v[154:157], v138
	ds_read_b128 v[164:167], v138 offset:1024
	ds_read_b128 v[168:171], v138 offset:2048
	ds_read_b128 v[172:175], v138 offset:3072
	s_add_u32 s18, s18, 0xb0000
	s_addc_u32 s19, s19, 0
	s_mov_b32 m0, s36
	v_lshl_add_u64 v[158:159], s[18:19], 0, v[144:145]
	ds_read_b128 v[176:179], v162 offset:32768
	ds_read_b128 v[180:183], v162 offset:33792
	ds_read_b128 v[184:187], v162 offset:34816
	ds_read_b128 v[188:191], v162 offset:35840
	ds_read_b128 v[192:195], v162 offset:36864
	ds_read_b128 v[196:199], v162 offset:37888
	ds_read_b128 v[200:203], v162 offset:38912
	ds_read_b128 v[204:207], v162 offset:39936
	global_load_lds_dwordx4 v[158:159], off
	v_lshl_add_u64 v[158:159], s[18:19], 0, v[146:147]
	s_mov_b32 m0, s37
	s_nop 0
	global_load_lds_dwordx4 v[158:159], off
	s_add_i32 s18, 16, 0x1c000
	v_add_u32_e32 v138, s18, v160
	ds_read_b128 v[208:211], v138
	ds_read_b128 v[212:215], v138 offset:1024
	ds_read_b128 v[216:219], v138 offset:2048
	ds_read_b128 v[220:223], v138 offset:3072
	s_waitcnt vmcnt(8) lgkmcnt(0)
	s_barrier
	v_mfma_f32_16x16x32_bf16 v[124:127], v[154:157], v[176:179], v[124:127]
	v_mfma_f32_16x16x32_bf16 v[120:123], v[168:171], v[176:179], v[120:123]
	v_mfma_f32_16x16x32_bf16 v[108:111], v[154:157], v[184:187], v[108:111]
	v_mfma_f32_16x16x32_bf16 v[104:107], v[168:171], v[184:187], v[104:107]
	v_mfma_f32_16x16x32_bf16 v[92:95], v[154:157], v[192:195], v[92:95]
	v_mfma_f32_16x16x32_bf16 v[88:91], v[168:171], v[192:195], v[88:91]
	v_mfma_f32_16x16x32_bf16 v[76:79], v[154:157], v[200:203], v[76:79]
	v_mfma_f32_16x16x32_bf16 v[72:75], v[168:171], v[200:203], v[72:75]
	v_mfma_f32_16x16x32_bf16 v[124:127], v[164:167], v[180:183], v[124:127]
	v_mfma_f32_16x16x32_bf16 v[120:123], v[172:175], v[180:183], v[120:123]
	v_mfma_f32_16x16x32_bf16 v[108:111], v[164:167], v[188:191], v[108:111]
	v_mfma_f32_16x16x32_bf16 v[104:107], v[172:175], v[188:191], v[104:107]
	v_mfma_f32_16x16x32_bf16 v[92:95], v[164:167], v[196:199], v[92:95]
	v_mfma_f32_16x16x32_bf16 v[88:91], v[172:175], v[196:199], v[88:91]
	v_mfma_f32_16x16x32_bf16 v[76:79], v[164:167], v[204:207], v[76:79]
	v_mfma_f32_16x16x32_bf16 v[72:75], v[172:175], v[204:207], v[72:75]
	v_mfma_f32_16x16x32_bf16 v[116:119], v[208:211], v[176:179], v[116:119]
	v_mfma_f32_16x16x32_bf16 v[112:115], v[216:219], v[176:179], v[112:115]
	v_mfma_f32_16x16x32_bf16 v[100:103], v[208:211], v[184:187], v[100:103]
	v_mfma_f32_16x16x32_bf16 v[96:99], v[216:219], v[184:187], v[96:99]
	v_mfma_f32_16x16x32_bf16 v[84:87], v[208:211], v[192:195], v[84:87]
	v_mfma_f32_16x16x32_bf16 v[80:83], v[216:219], v[192:195], v[80:83]
	v_mfma_f32_16x16x32_bf16 v[68:71], v[208:211], v[200:203], v[68:71]
	v_mfma_f32_16x16x32_bf16 v[64:67], v[216:219], v[200:203], v[64:67]
	v_mfma_f32_16x16x32_bf16 v[116:119], v[212:215], v[180:183], v[116:119]
	v_mfma_f32_16x16x32_bf16 v[112:115], v[220:223], v[180:183], v[112:115]
	v_mfma_f32_16x16x32_bf16 v[100:103], v[212:215], v[188:191], v[100:103]
	v_mfma_f32_16x16x32_bf16 v[96:99], v[220:223], v[188:191], v[96:99]
	v_mfma_f32_16x16x32_bf16 v[84:87], v[212:215], v[196:199], v[84:87]
	v_mfma_f32_16x16x32_bf16 v[80:83], v[220:223], v[196:199], v[80:83]
	v_mfma_f32_16x16x32_bf16 v[68:71], v[212:215], v[204:207], v[68:71]
	v_mfma_f32_16x16x32_bf16 v[64:67], v[220:223], v[204:207], v[64:67]
	s_barrier
	ds_read_b128 v[176:179], v162 offset:49152
	ds_read_b128 v[180:183], v162 offset:50176
	ds_read_b128 v[184:187], v162 offset:51200
	ds_read_b128 v[188:191], v162 offset:52224
	ds_read_b128 v[192:195], v162 offset:53248
	ds_read_b128 v[196:199], v162 offset:54272
	ds_read_b128 v[200:203], v162 offset:55296
	ds_read_b128 v[204:207], v162 offset:56320
	s_add_i32 s19, s20, s5
	v_lshl_add_u64 v[130:131], v[130:131], 0, s[28:29]
	s_mov_b32 m0, s19
	s_nop 0
	global_load_lds_dwordx4 v[130:131], off
	v_lshl_add_u64 v[130:131], v[132:133], 0, s[28:29]
	s_add_i32 m0, s19, 0x2000
	s_nop 0
	global_load_lds_dwordx4 v[130:131], off
	s_mov_b32 m0, s44
	v_lshl_add_u64 v[130:131], v[134:135], 0, s[28:29]
	global_load_lds_dwordx4 v[130:131], off
	v_lshl_add_u64 v[130:131], v[136:137], 0, s[28:29]
	s_mov_b32 m0, s45
	s_nop 0
	global_load_lds_dwordx4 v[130:131], off
	s_add_u32 s14, s14, 0xb0080
	s_addc_u32 s15, s15, 0
	s_add_i32 s18, s18, s5
	v_lshl_add_u64 v[130:131], s[14:15], 0, v[128:129]
	s_mov_b32 m0, s18
	s_nop 0
	global_load_lds_dwordx4 v[130:131], off
	v_lshl_add_u64 v[130:131], s[14:15], 0, v[148:149]
	s_add_i32 m0, s18, 0x2000
	s_nop 0
	global_load_lds_dwordx4 v[130:131], off
	s_waitcnt vmcnt(8) lgkmcnt(0)
	s_barrier
	v_mfma_f32_16x16x32_bf16 v[60:63], v[154:157], v[176:179], v[60:63]
	v_mfma_f32_16x16x32_bf16 v[56:59], v[168:171], v[176:179], v[56:59]
	v_mfma_f32_16x16x32_bf16 v[44:47], v[154:157], v[184:187], v[44:47]
	v_mfma_f32_16x16x32_bf16 v[40:43], v[168:171], v[184:187], v[40:43]
	v_mfma_f32_16x16x32_bf16 v[28:31], v[154:157], v[192:195], v[28:31]
	v_mfma_f32_16x16x32_bf16 v[24:27], v[168:171], v[192:195], v[24:27]
	v_mfma_f32_16x16x32_bf16 v[12:15], v[154:157], v[200:203], v[12:15]
	v_mfma_f32_16x16x32_bf16 v[8:11], v[168:171], v[200:203], v[8:11]
	v_mfma_f32_16x16x32_bf16 v[60:63], v[164:167], v[180:183], v[60:63]
	v_mfma_f32_16x16x32_bf16 v[56:59], v[172:175], v[180:183], v[56:59]
	v_mfma_f32_16x16x32_bf16 v[44:47], v[164:167], v[188:191], v[44:47]
	v_mfma_f32_16x16x32_bf16 v[40:43], v[172:175], v[188:191], v[40:43]
	v_mfma_f32_16x16x32_bf16 v[28:31], v[164:167], v[196:199], v[28:31]
	v_mfma_f32_16x16x32_bf16 v[24:27], v[172:175], v[196:199], v[24:27]
	v_mfma_f32_16x16x32_bf16 v[12:15], v[164:167], v[204:207], v[12:15]
	v_mfma_f32_16x16x32_bf16 v[8:11], v[172:175], v[204:207], v[8:11]
	v_mfma_f32_16x16x32_bf16 v[52:55], v[208:211], v[176:179], v[52:55]
	v_mfma_f32_16x16x32_bf16 v[48:51], v[216:219], v[176:179], v[48:51]
	v_mfma_f32_16x16x32_bf16 v[36:39], v[208:211], v[184:187], v[36:39]
	v_mfma_f32_16x16x32_bf16 v[32:35], v[216:219], v[184:187], v[32:35]
	v_mfma_f32_16x16x32_bf16 v[20:23], v[208:211], v[192:195], v[20:23]
	v_mfma_f32_16x16x32_bf16 v[16:19], v[216:219], v[192:195], v[16:19]
	v_mfma_f32_16x16x32_bf16 v[4:7], v[208:211], v[200:203], v[4:7]
	v_mfma_f32_16x16x32_bf16 v[0:3], v[216:219], v[200:203], v[0:3]
	v_mfma_f32_16x16x32_bf16 v[52:55], v[212:215], v[180:183], v[52:55]
	v_mfma_f32_16x16x32_bf16 v[48:51], v[220:223], v[180:183], v[48:51]
	v_mfma_f32_16x16x32_bf16 v[36:39], v[212:215], v[188:191], v[36:39]
	v_mfma_f32_16x16x32_bf16 v[32:35], v[220:223], v[188:191], v[32:35]
	v_mfma_f32_16x16x32_bf16 v[20:23], v[212:215], v[196:199], v[20:23]
	v_mfma_f32_16x16x32_bf16 v[16:19], v[220:223], v[196:199], v[16:19]
	v_mfma_f32_16x16x32_bf16 v[4:7], v[212:215], v[204:207], v[4:7]
	v_mfma_f32_16x16x32_bf16 v[0:3], v[220:223], v[204:207], v[0:3]
	s_add_i32 s25, s25, 2
	s_add_u32 s30, s30, 0x100
	s_addc_u32 s31, s31, 0
	s_add_u32 s0, s0, 0x100
	s_addc_u32 s1, s1, 0
	s_cmp_gt_u32 s25, 41
	s_cbranch_scc1 .Lg2_exit
	s_branch .Lg2_head

.Lg2_epi:
	s_setprio 0
	s_nop 0
	s_nop 0
	s_nop 0
	s_nop 0
	s_nop 0
	s_nop 0
	s_nop 0
	s_cmp_lt_i32 s47, 0
	s_cselect_b64 s[14:15], -1, 0
	s_cmp_gt_i32 s47, -1
	s_cbranch_scc1 .LBB0_348
	v_mul_f32_e32 v131, 0x3d372713, v120
	v_mul_f32_e32 v131, v120, v131
	v_fma_f32 v131, v120, v131, v120
	v_mul_f32_e32 v131, 0x3fcc422a, v131
	v_mul_f32_e32 v131, 0xbfb8aa3b, v131
	v_exp_f32_e32 v131, v131
	v_mul_f32_e32 v130, 0x3d372713, v124
	v_mul_f32_e32 v130, v124, v130
	v_fma_f32 v130, v124, v130, v124
	v_add_f32_e32 v131, 1.0, v131
	v_rcp_f32_e32 v132, v131
	v_mul_f32_e32 v131, 0x3d372713, v125
	v_mul_f32_e32 v131, v125, v131
	v_fma_f32 v131, v125, v131, v125
	v_mul_f32_e32 v130, 0x3fcc422a, v130
	v_mul_f32_e32 v131, 0x3fcc422a, v131
	v_mul_f32_e32 v130, 0xbfb8aa3b, v130
	v_mul_f32_e32 v131, 0xbfb8aa3b, v131
	v_mul_f32_e32 v135, 0x3d372713, v122
	v_exp_f32_e32 v130, v130
	v_exp_f32_e32 v131, v131
	v_mul_f32_e32 v135, v122, v135
	v_fma_f32 v135, v122, v135, v122
	v_mul_f32_e32 v135, 0x3fcc422a, v135
	v_mul_f32_e32 v135, 0xbfb8aa3b, v135
	v_add_f32_e32 v130, 1.0, v130
	v_add_f32_e32 v131, 1.0, v131
	v_exp_f32_e32 v135, v135
	v_rcp_f32_e32 v130, v130
	v_rcp_f32_e32 v131, v131
	v_mul_f32_e32 v133, 0x3d372713, v121
	v_add_f32_e32 v135, 1.0, v135
	v_mul_f32_e32 v134, 0x3d372713, v126
	v_rcp_f32_e32 v136, v135
	v_mul_f32_e32 v135, 0x3d372713, v127
	v_pk_mul_f32 v[124:125], v[124:125], v[130:131]
	v_mul_f32_e32 v130, 0x3d372713, v123
	v_mul_f32_e32 v133, v121, v133
	v_mul_f32_e32 v134, v126, v134
	v_mul_f32_e32 v135, v127, v135
	v_mul_f32_e32 v130, v123, v130
	v_fma_f32 v133, v121, v133, v121
	v_fma_f32 v134, v126, v134, v126
	v_fma_f32 v135, v127, v135, v127
	v_fma_f32 v130, v123, v130, v123
	v_mul_f32_e32 v133, 0x3fcc422a, v133
	v_mul_f32_e32 v134, 0x3fcc422a, v134
	v_mul_f32_e32 v135, 0x3fcc422a, v135
	v_mul_f32_e32 v130, 0x3fcc422a, v130
	v_mul_f32_e32 v133, 0xbfb8aa3b, v133
	v_mul_f32_e32 v134, 0xbfb8aa3b, v134
	v_mul_f32_e32 v135, 0xbfb8aa3b, v135
	v_mul_f32_e32 v130, 0xbfb8aa3b, v130
	v_exp_f32_e32 v133, v133
	v_exp_f32_e32 v134, v134
	v_exp_f32_e32 v135, v135
	v_exp_f32_e32 v130, v130
	v_add_f32_e32 v133, 1.0, v133
	v_add_f32_e32 v134, 1.0, v134
	v_add_f32_e32 v135, 1.0, v135
	v_add_f32_e32 v130, 1.0, v130
	v_rcp_f32_e32 v133, v133
	v_rcp_f32_e32 v134, v134
	v_rcp_f32_e32 v135, v135
	v_rcp_f32_e32 v137, v130
	v_pk_mul_f32 v[120:121], v[120:121], v[132:133]
	v_pk_mul_f32 v[126:127], v[126:127], v[134:135]
	v_pk_mul_f32 v[122:123], v[122:123], v[136:137]

.LBB0_390:
	v_mov_b64_e32 v[0:1], 0x1080
	s_ashr_i32 s13, s12, 31
	v_cmp_lt_i64_e32 vcc, s[30:31], v[0:1]
	s_lshl_b64 s[24:25], s[12:13], 19
	v_readlane_b32 s30, v252, 55
	v_readlane_b32 s31, v252, 56
	s_add_u32 s40, s30, s24
	s_addc_u32 s41, s31, s25
	v_lshl_add_u32 v154, s20, 8, v143
	v_readlane_b32 s30, v252, 43
	v_ashrrev_i32_e32 v155, 31, v154
	v_readlane_b32 s31, v252, 44
	s_and_b64 s[24:25], vcc, exec
	s_cselect_b32 s1, s41, s19
	v_lshl_add_u64 v[0:1], v[154:155], 2, s[30:31]
	global_load_dword v165, v[0:1], off
	global_load_dword v164, v[0:1], off offset:64
	global_load_dword v163, v[0:1], off offset:128
	global_load_dword v162, v[0:1], off offset:192
	global_load_dword v161, v[0:1], off offset:512
	global_load_dword v160, v[0:1], off offset:576
	global_load_dword v159, v[0:1], off offset:640
	global_load_dword v155, v[0:1], off offset:704
	s_cselect_b32 s13, s40, s18
	s_ashr_i32 s9, s8, 31
	s_lshl_b64 s[24:25], s[8:9], 19
	s_add_u32 s42, s16, s24
	s_addc_u32 s43, s17, s25
	s_and_b64 s[24:25], vcc, exec
	s_cselect_b32 s9, s43, s15
	s_cselect_b32 s24, s42, s14
	s_add_u32 s30, s18, 0x40080
	s_addc_u32 s31, s19, 0
	s_add_u32 s25, s14, 0x100
	v_mov_b32_e32 v8, 0
	s_addc_u32 s47, s15, 0
	s_mov_b32 s92, -2
	v_mov_b32_e32 v9, v8
	v_mov_b32_e32 v10, v8
	v_mov_b32_e32 v11, v8
	v_mov_b32_e32 v12, v8
	v_mov_b32_e32 v13, v8
	v_mov_b32_e32 v14, v8
	v_mov_b32_e32 v15, v8
	v_mov_b32_e32 v24, v8
	v_mov_b32_e32 v25, v8
	v_mov_b32_e32 v26, v8
	v_mov_b32_e32 v27, v8
	v_mov_b32_e32 v28, v8
	v_mov_b32_e32 v29, v8
	v_mov_b32_e32 v30, v8
	v_mov_b32_e32 v31, v8
	v_mov_b32_e32 v40, v8
	v_mov_b32_e32 v41, v8
	v_mov_b32_e32 v42, v8
	v_mov_b32_e32 v43, v8
	v_mov_b32_e32 v44, v8
	v_mov_b32_e32 v45, v8
	v_mov_b32_e32 v46, v8
	v_mov_b32_e32 v47, v8
	v_mov_b32_e32 v56, v8
	v_mov_b32_e32 v57, v8
	v_mov_b32_e32 v58, v8
	v_mov_b32_e32 v59, v8
	v_mov_b32_e32 v60, v8
	v_mov_b32_e32 v61, v8
	v_mov_b32_e32 v62, v8
	v_mov_b32_e32 v63, v8
	v_mov_b32_e32 v0, v8
	v_mov_b32_e32 v1, v8
	v_mov_b32_e32 v2, v8
	v_mov_b32_e32 v3, v8
	v_mov_b32_e32 v4, v8
	v_mov_b32_e32 v5, v8
	v_mov_b32_e32 v6, v8
	v_mov_b32_e32 v7, v8
	v_mov_b32_e32 v16, v8
	v_mov_b32_e32 v17, v8
	v_mov_b32_e32 v18, v8
	v_mov_b32_e32 v19, v8
	v_mov_b32_e32 v20, v8
	v_mov_b32_e32 v21, v8
	v_mov_b32_e32 v22, v8
	v_mov_b32_e32 v23, v8
	v_mov_b32_e32 v32, v8
	v_mov_b32_e32 v33, v8
	v_mov_b32_e32 v34, v8
	v_mov_b32_e32 v35, v8
	v_mov_b32_e32 v36, v8
	v_mov_b32_e32 v37, v8
	v_mov_b32_e32 v38, v8
	v_mov_b32_e32 v39, v8
	v_mov_b32_e32 v48, v8
	v_mov_b32_e32 v49, v8
	v_mov_b32_e32 v50, v8
	v_mov_b32_e32 v51, v8
	v_mov_b32_e32 v52, v8
	v_mov_b32_e32 v53, v8
	v_mov_b32_e32 v54, v8
	v_mov_b32_e32 v55, v8
	v_mov_b32_e32 v72, v8
	v_mov_b32_e32 v73, v8
	v_mov_b32_e32 v74, v8
	v_mov_b32_e32 v75, v8
	v_mov_b32_e32 v76, v8
	v_mov_b32_e32 v77, v8
	v_mov_b32_e32 v78, v8
	v_mov_b32_e32 v79, v8
	v_mov_b32_e32 v88, v8
	v_mov_b32_e32 v89, v8
	v_mov_b32_e32 v90, v8
	v_mov_b32_e32 v91, v8
	v_mov_b32_e32 v92, v8
	v_mov_b32_e32 v93, v8
	v_mov_b32_e32 v94, v8
	v_mov_b32_e32 v95, v8
	v_mov_b32_e32 v104, v8
	v_mov_b32_e32 v105, v8
	v_mov_b32_e32 v106, v8
	v_mov_b32_e32 v107, v8
	v_mov_b32_e32 v108, v8
	v_mov_b32_e32 v109, v8
	v_mov_b32_e32 v110, v8
	v_mov_b32_e32 v111, v8
	v_mov_b32_e32 v120, v8
	v_mov_b32_e32 v121, v8
	v_mov_b32_e32 v122, v8
	v_mov_b32_e32 v123, v8
	v_mov_b32_e32 v124, v8
	v_mov_b32_e32 v125, v8
	v_mov_b32_e32 v126, v8
	v_mov_b32_e32 v127, v8
	v_mov_b32_e32 v64, v8
	v_mov_b32_e32 v65, v8
	v_mov_b32_e32 v66, v8
	v_mov_b32_e32 v67, v8
	v_mov_b32_e32 v68, v8
	v_mov_b32_e32 v69, v8
	v_mov_b32_e32 v70, v8
	v_mov_b32_e32 v71, v8
	v_mov_b32_e32 v80, v8
	v_mov_b32_e32 v81, v8
	v_mov_b32_e32 v82, v8
	v_mov_b32_e32 v83, v8
	v_mov_b32_e32 v84, v8
	v_mov_b32_e32 v85, v8
	v_mov_b32_e32 v86, v8
	v_mov_b32_e32 v87, v8
	v_mov_b32_e32 v96, v8
	v_mov_b32_e32 v97, v8
	v_mov_b32_e32 v98, v8
	v_mov_b32_e32 v99, v8
	v_mov_b32_e32 v100, v8
	v_mov_b32_e32 v101, v8
	v_mov_b32_e32 v102, v8
	v_mov_b32_e32 v103, v8
	v_mov_b32_e32 v112, v8
	v_mov_b32_e32 v113, v8
	v_mov_b32_e32 v114, v8
	v_mov_b32_e32 v115, v8
	v_mov_b32_e32 v116, v8
	v_mov_b32_e32 v117, v8
	v_mov_b32_e32 v118, v8
	v_mov_b32_e32 v119, v8
	s_cmpk_gt_u32 s4, 0xff
	s_cbranch_scc0 .Lg1_enter
	s_setprio 1

.Lg1_enter:
.LBB0_391:
	s_add_u32 s14, s30, 0xfffc0080
	s_addc_u32 s15, s31, -1
	s_add_i32 s20, 16, 0x10000
	v_add_u32_e32 v130, s20, v156
	ds_read_b128 v[166:169], v130
	ds_read_b128 v[170:173], v130 offset:1024
	ds_read_b128 v[174:177], v130 offset:2048
	ds_read_b128 v[178:181], v130 offset:3072
	s_cmp_eq_u32 s92, 12
	s_cselect_b32 s19, s1, s15
	s_cselect_b32 s18, s13, s14
	s_cselect_b32 s15, s9, s47
	s_cselect_b32 s14, s24, s25
	v_lshl_add_u64 v[130:131], s[30:31], 0, v[150:151]
	s_add_i32 m0, s34, 0xc000
	ds_read_b128 v[182:185], v158
	ds_read_b128 v[186:189], v158 offset:1024
	ds_read_b128 v[190:193], v158 offset:2048
	ds_read_b128 v[194:197], v158 offset:3072
	ds_read_b128 v[198:201], v158 offset:4096
	ds_read_b128 v[202:205], v158 offset:5120
	ds_read_b128 v[206:209], v158 offset:6144
	ds_read_b128 v[210:213], v158 offset:7168
	global_load_lds_dwordx4 v[130:131], off
	v_lshl_add_u64 v[130:131], s[30:31], 0, v[152:153]
	s_add_i32 m0, s34, 0xe000
	s_nop 0
	global_load_lds_dwordx4 v[130:131], off
	s_add_i32 s50, 16, 0x14000
	v_add_u32_e32 v130, s50, v156
	ds_read_b128 v[214:217], v130
	ds_read_b128 v[218:221], v130 offset:1024
	ds_read_b128 v[222:225], v130 offset:2048
	ds_read_b128 v[226:229], v130 offset:3072
	s_waitcnt vmcnt(8) lgkmcnt(0)
	s_barrier
	v_mfma_f32_16x16x32_bf16 v[116:119], v[166:169], v[182:185], v[116:119]
	v_mfma_f32_16x16x32_bf16 v[112:115], v[174:177], v[182:185], v[112:115]
	v_mfma_f32_16x16x32_bf16 v[100:103], v[166:169], v[190:193], v[100:103]
	v_mfma_f32_16x16x32_bf16 v[96:99], v[174:177], v[190:193], v[96:99]
	v_mfma_f32_16x16x32_bf16 v[84:87], v[166:169], v[198:201], v[84:87]
	v_mfma_f32_16x16x32_bf16 v[80:83], v[174:177], v[198:201], v[80:83]
	v_mfma_f32_16x16x32_bf16 v[68:71], v[166:169], v[206:209], v[68:71]
	v_mfma_f32_16x16x32_bf16 v[64:67], v[174:177], v[206:209], v[64:67]
	v_mfma_f32_16x16x32_bf16 v[116:119], v[170:173], v[186:189], v[116:119]
	v_mfma_f32_16x16x32_bf16 v[112:115], v[178:181], v[186:189], v[112:115]
	v_mfma_f32_16x16x32_bf16 v[100:103], v[170:173], v[194:197], v[100:103]
	v_mfma_f32_16x16x32_bf16 v[96:99], v[178:181], v[194:197], v[96:99]
	v_mfma_f32_16x16x32_bf16 v[84:87], v[170:173], v[202:205], v[84:87]
	v_mfma_f32_16x16x32_bf16 v[80:83], v[178:181], v[202:205], v[80:83]
	v_mfma_f32_16x16x32_bf16 v[68:71], v[170:173], v[210:213], v[68:71]
	v_mfma_f32_16x16x32_bf16 v[64:67], v[178:181], v[210:213], v[64:67]
	v_mfma_f32_16x16x32_bf16 v[124:127], v[214:217], v[182:185], v[124:127]
	v_mfma_f32_16x16x32_bf16 v[120:123], v[222:225], v[182:185], v[120:123]
	v_mfma_f32_16x16x32_bf16 v[108:111], v[214:217], v[190:193], v[108:111]
	v_mfma_f32_16x16x32_bf16 v[104:107], v[222:225], v[190:193], v[104:107]
	v_mfma_f32_16x16x32_bf16 v[92:95], v[214:217], v[198:201], v[92:95]
	v_mfma_f32_16x16x32_bf16 v[88:91], v[222:225], v[198:201], v[88:91]
	v_mfma_f32_16x16x32_bf16 v[76:79], v[214:217], v[206:209], v[76:79]
	v_mfma_f32_16x16x32_bf16 v[72:75], v[222:225], v[206:209], v[72:75]
	v_mfma_f32_16x16x32_bf16 v[124:127], v[218:221], v[186:189], v[124:127]
	v_mfma_f32_16x16x32_bf16 v[120:123], v[226:229], v[186:189], v[120:123]
	v_mfma_f32_16x16x32_bf16 v[108:111], v[218:221], v[194:197], v[108:111]
	v_mfma_f32_16x16x32_bf16 v[104:107], v[226:229], v[194:197], v[104:107]
	v_mfma_f32_16x16x32_bf16 v[92:95], v[218:221], v[202:205], v[92:95]
	v_mfma_f32_16x16x32_bf16 v[88:91], v[226:229], v[202:205], v[88:91]
	v_mfma_f32_16x16x32_bf16 v[76:79], v[218:221], v[210:213], v[76:79]
	v_mfma_f32_16x16x32_bf16 v[72:75], v[226:229], v[210:213], v[72:75]
	s_barrier
	ds_read_b128 v[182:185], v158 offset:16384
	ds_read_b128 v[186:189], v158 offset:17408
	ds_read_b128 v[190:193], v158 offset:18432
	ds_read_b128 v[194:197], v158 offset:19456
	ds_read_b128 v[198:201], v158 offset:20480
	ds_read_b128 v[202:205], v158 offset:21504
	ds_read_b128 v[206:209], v158 offset:22528
	ds_read_b128 v[210:213], v158 offset:23552
	s_add_i32 s20, s20, s5
	v_lshl_add_u64 v[130:131], s[14:15], 0, v[128:129]
	s_mov_b32 m0, s20
	v_lshl_add_u64 v[132:133], s[14:15], 0, v[144:145]
	global_load_lds_dwordx4 v[130:131], off
	s_add_i32 m0, s20, 0x2000
	s_nop 0
	global_load_lds_dwordx4 v[132:133], off
	s_mov_b32 m0, s34
	v_lshl_add_u64 v[134:135], s[18:19], 0, v[148:149]
	global_load_lds_dwordx4 v[134:135], off
	v_lshl_add_u64 v[136:137], s[18:19], 0, v[146:147]
	s_mov_b32 m0, s35
	s_nop 0
	global_load_lds_dwordx4 v[136:137], off
	s_add_u32 s48, s14, 0x40000
	s_addc_u32 s49, s15, 0
	s_add_i32 s20, s50, s5
	v_lshl_add_u64 v[138:139], s[48:49], 0, v[128:129]
	s_mov_b32 m0, s20
	s_nop 0
	global_load_lds_dwordx4 v[138:139], off
	v_lshl_add_u64 v[138:139], s[48:49], 0, v[144:145]
	s_add_i32 m0, s20, 0x2000
	s_nop 0
	global_load_lds_dwordx4 v[138:139], off
	s_waitcnt vmcnt(8) lgkmcnt(0)
	s_barrier
	v_mfma_f32_16x16x32_bf16 v[52:55], v[166:169], v[182:185], v[52:55]
	v_mfma_f32_16x16x32_bf16 v[48:51], v[174:177], v[182:185], v[48:51]
	v_mfma_f32_16x16x32_bf16 v[36:39], v[166:169], v[190:193], v[36:39]
	v_mfma_f32_16x16x32_bf16 v[32:35], v[174:177], v[190:193], v[32:35]
	v_mfma_f32_16x16x32_bf16 v[20:23], v[166:169], v[198:201], v[20:23]
	v_mfma_f32_16x16x32_bf16 v[16:19], v[174:177], v[198:201], v[16:19]
	v_mfma_f32_16x16x32_bf16 v[4:7], v[166:169], v[206:209], v[4:7]
	v_mfma_f32_16x16x32_bf16 v[0:3], v[174:177], v[206:209], v[0:3]
	v_mfma_f32_16x16x32_bf16 v[52:55], v[170:173], v[186:189], v[52:55]
	v_mfma_f32_16x16x32_bf16 v[48:51], v[178:181], v[186:189], v[48:51]
	v_mfma_f32_16x16x32_bf16 v[36:39], v[170:173], v[194:197], v[36:39]
	v_mfma_f32_16x16x32_bf16 v[32:35], v[178:181], v[194:197], v[32:35]
	v_mfma_f32_16x16x32_bf16 v[20:23], v[170:173], v[202:205], v[20:23]
	v_mfma_f32_16x16x32_bf16 v[16:19], v[178:181], v[202:205], v[16:19]
	v_mfma_f32_16x16x32_bf16 v[4:7], v[170:173], v[210:213], v[4:7]
	v_mfma_f32_16x16x32_bf16 v[0:3], v[178:181], v[210:213], v[0:3]
	v_mfma_f32_16x16x32_bf16 v[60:63], v[214:217], v[182:185], v[60:63]
	v_mfma_f32_16x16x32_bf16 v[56:59], v[222:225], v[182:185], v[56:59]
	v_mfma_f32_16x16x32_bf16 v[44:47], v[214:217], v[190:193], v[44:47]
	v_mfma_f32_16x16x32_bf16 v[40:43], v[222:225], v[190:193], v[40:43]
	v_mfma_f32_16x16x32_bf16 v[28:31], v[214:217], v[198:201], v[28:31]
	v_mfma_f32_16x16x32_bf16 v[24:27], v[222:225], v[198:201], v[24:27]
	v_mfma_f32_16x16x32_bf16 v[12:15], v[214:217], v[206:209], v[12:15]
	v_mfma_f32_16x16x32_bf16 v[8:11], v[222:225], v[206:209], v[8:11]
	v_mfma_f32_16x16x32_bf16 v[60:63], v[218:221], v[186:189], v[60:63]
	v_mfma_f32_16x16x32_bf16 v[56:59], v[226:229], v[186:189], v[56:59]
	v_mfma_f32_16x16x32_bf16 v[44:47], v[218:221], v[194:197], v[44:47]
	v_mfma_f32_16x16x32_bf16 v[40:43], v[226:229], v[194:197], v[40:43]
	v_mfma_f32_16x16x32_bf16 v[28:31], v[218:221], v[202:205], v[28:31]
	v_mfma_f32_16x16x32_bf16 v[24:27], v[226:229], v[202:205], v[24:27]
	v_mfma_f32_16x16x32_bf16 v[12:15], v[218:221], v[210:213], v[12:15]
	v_mfma_f32_16x16x32_bf16 v[8:11], v[226:229], v[210:213], v[8:11]
	s_add_i32 s20, 16, 0x18000
	v_add_u32_e32 v138, s20, v156
	s_barrier
	ds_read_b128 v[166:169], v138
	ds_read_b128 v[170:173], v138 offset:1024
	ds_read_b128 v[174:177], v138 offset:2048
	ds_read_b128 v[178:181], v138 offset:3072
	s_add_u32 s18, s18, 0x40000
	s_addc_u32 s19, s19, 0
	s_mov_b32 m0, s36
	v_lshl_add_u64 v[214:215], s[18:19], 0, v[148:149]
	ds_read_b128 v[182:185], v158 offset:32768
	ds_read_b128 v[186:189], v158 offset:33792
	ds_read_b128 v[190:193], v158 offset:34816
	ds_read_b128 v[194:197], v158 offset:35840
	ds_read_b128 v[198:201], v158 offset:36864
	ds_read_b128 v[202:205], v158 offset:37888
	ds_read_b128 v[206:209], v158 offset:38912
	ds_read_b128 v[210:213], v158 offset:39936
	global_load_lds_dwordx4 v[214:215], off
	v_lshl_add_u64 v[214:215], s[18:19], 0, v[146:147]
	s_mov_b32 m0, s37
	s_nop 0
	global_load_lds_dwordx4 v[214:215], off
	s_add_i32 s18, 16, 0x1c000
	v_add_u32_e32 v138, s18, v156
	ds_read_b128 v[214:217], v138
	ds_read_b128 v[218:221], v138 offset:1024
	ds_read_b128 v[222:225], v138 offset:2048
	ds_read_b128 v[226:229], v138 offset:3072
	s_waitcnt vmcnt(8) lgkmcnt(0)
	s_barrier
	v_mfma_f32_16x16x32_bf16 v[116:119], v[166:169], v[182:185], v[116:119]
	v_mfma_f32_16x16x32_bf16 v[112:115], v[174:177], v[182:185], v[112:115]
	v_mfma_f32_16x16x32_bf16 v[100:103], v[166:169], v[190:193], v[100:103]
	v_mfma_f32_16x16x32_bf16 v[96:99], v[174:177], v[190:193], v[96:99]
	v_mfma_f32_16x16x32_bf16 v[84:87], v[166:169], v[198:201], v[84:87]
	v_mfma_f32_16x16x32_bf16 v[80:83], v[174:177], v[198:201], v[80:83]
	v_mfma_f32_16x16x32_bf16 v[68:71], v[166:169], v[206:209], v[68:71]
	v_mfma_f32_16x16x32_bf16 v[64:67], v[174:177], v[206:209], v[64:67]
	v_mfma_f32_16x16x32_bf16 v[116:119], v[170:173], v[186:189], v[116:119]
	v_mfma_f32_16x16x32_bf16 v[112:115], v[178:181], v[186:189], v[112:115]
	v_mfma_f32_16x16x32_bf16 v[100:103], v[170:173], v[194:197], v[100:103]
	v_mfma_f32_16x16x32_bf16 v[96:99], v[178:181], v[194:197], v[96:99]
	v_mfma_f32_16x16x32_bf16 v[84:87], v[170:173], v[202:205], v[84:87]
	v_mfma_f32_16x16x32_bf16 v[80:83], v[178:181], v[202:205], v[80:83]
	v_mfma_f32_16x16x32_bf16 v[68:71], v[170:173], v[210:213], v[68:71]
	v_mfma_f32_16x16x32_bf16 v[64:67], v[178:181], v[210:213], v[64:67]
	v_mfma_f32_16x16x32_bf16 v[124:127], v[214:217], v[182:185], v[124:127]
	v_mfma_f32_16x16x32_bf16 v[120:123], v[222:225], v[182:185], v[120:123]
	v_mfma_f32_16x16x32_bf16 v[108:111], v[214:217], v[190:193], v[108:111]
	v_mfma_f32_16x16x32_bf16 v[104:107], v[222:225], v[190:193], v[104:107]
	v_mfma_f32_16x16x32_bf16 v[92:95], v[214:217], v[198:201], v[92:95]
	v_mfma_f32_16x16x32_bf16 v[88:91], v[222:225], v[198:201], v[88:91]
	v_mfma_f32_16x16x32_bf16 v[76:79], v[214:217], v[206:209], v[76:79]
	v_mfma_f32_16x16x32_bf16 v[72:75], v[222:225], v[206:209], v[72:75]
	v_mfma_f32_16x16x32_bf16 v[124:127], v[218:221], v[186:189], v[124:127]
	v_mfma_f32_16x16x32_bf16 v[120:123], v[226:229], v[186:189], v[120:123]
	v_mfma_f32_16x16x32_bf16 v[108:111], v[218:221], v[194:197], v[108:111]
	v_mfma_f32_16x16x32_bf16 v[104:107], v[226:229], v[194:197], v[104:107]
	v_mfma_f32_16x16x32_bf16 v[92:95], v[218:221], v[202:205], v[92:95]
	v_mfma_f32_16x16x32_bf16 v[88:91], v[226:229], v[202:205], v[88:91]
	v_mfma_f32_16x16x32_bf16 v[76:79], v[218:221], v[210:213], v[76:79]
	v_mfma_f32_16x16x32_bf16 v[72:75], v[226:229], v[210:213], v[72:75]
	s_barrier
	ds_read_b128 v[182:185], v158 offset:49152
	ds_read_b128 v[186:189], v158 offset:50176
	ds_read_b128 v[190:193], v158 offset:51200
	ds_read_b128 v[194:197], v158 offset:52224
	ds_read_b128 v[198:201], v158 offset:53248
	ds_read_b128 v[202:205], v158 offset:54272
	ds_read_b128 v[206:209], v158 offset:55296
	ds_read_b128 v[210:213], v158 offset:56320
	s_add_i32 s19, s20, s5
	v_lshl_add_u64 v[130:131], v[130:131], 0, s[28:29]
	s_mov_b32 m0, s19
	s_nop 0
	global_load_lds_dwordx4 v[130:131], off
	v_lshl_add_u64 v[130:131], v[132:133], 0, s[28:29]
	s_add_i32 m0, s19, 0x2000
	s_nop 0
	global_load_lds_dwordx4 v[130:131], off
	s_mov_b32 m0, s44
	v_lshl_add_u64 v[130:131], v[134:135], 0, s[28:29]
	global_load_lds_dwordx4 v[130:131], off
	v_lshl_add_u64 v[130:131], v[136:137], 0, s[28:29]
	s_mov_b32 m0, s45
	s_nop 0
	global_load_lds_dwordx4 v[130:131], off
	s_add_u32 s14, s14, 0x40080
	s_addc_u32 s15, s15, 0
	s_add_i32 s18, s18, s5
	v_lshl_add_u64 v[130:131], s[14:15], 0, v[128:129]
	s_mov_b32 m0, s18
	s_nop 0
	global_load_lds_dwordx4 v[130:131], off
	v_lshl_add_u64 v[130:131], s[14:15], 0, v[144:145]
	s_add_i32 m0, s18, 0x2000
	s_nop 0
	global_load_lds_dwordx4 v[130:131], off
	s_waitcnt vmcnt(8) lgkmcnt(0)
	s_barrier
	v_mfma_f32_16x16x32_bf16 v[52:55], v[166:169], v[182:185], v[52:55]
	v_mfma_f32_16x16x32_bf16 v[48:51], v[174:177], v[182:185], v[48:51]
	v_mfma_f32_16x16x32_bf16 v[36:39], v[166:169], v[190:193], v[36:39]
	v_mfma_f32_16x16x32_bf16 v[32:35], v[174:177], v[190:193], v[32:35]
	v_mfma_f32_16x16x32_bf16 v[20:23], v[166:169], v[198:201], v[20:23]
	v_mfma_f32_16x16x32_bf16 v[16:19], v[174:177], v[198:201], v[16:19]
	v_mfma_f32_16x16x32_bf16 v[4:7], v[166:169], v[206:209], v[4:7]
	v_mfma_f32_16x16x32_bf16 v[0:3], v[174:177], v[206:209], v[0:3]
	v_mfma_f32_16x16x32_bf16 v[52:55], v[170:173], v[186:189], v[52:55]
	v_mfma_f32_16x16x32_bf16 v[48:51], v[178:181], v[186:189], v[48:51]
	v_mfma_f32_16x16x32_bf16 v[36:39], v[170:173], v[194:197], v[36:39]
	v_mfma_f32_16x16x32_bf16 v[32:35], v[178:181], v[194:197], v[32:35]
	v_mfma_f32_16x16x32_bf16 v[20:23], v[170:173], v[202:205], v[20:23]
	v_mfma_f32_16x16x32_bf16 v[16:19], v[178:181], v[202:205], v[16:19]
	v_mfma_f32_16x16x32_bf16 v[4:7], v[170:173], v[210:213], v[4:7]
	v_mfma_f32_16x16x32_bf16 v[0:3], v[178:181], v[210:213], v[0:3]
	v_mfma_f32_16x16x32_bf16 v[60:63], v[214:217], v[182:185], v[60:63]
	v_mfma_f32_16x16x32_bf16 v[56:59], v[222:225], v[182:185], v[56:59]
	v_mfma_f32_16x16x32_bf16 v[44:47], v[214:217], v[190:193], v[44:47]
	v_mfma_f32_16x16x32_bf16 v[40:43], v[222:225], v[190:193], v[40:43]
	v_mfma_f32_16x16x32_bf16 v[28:31], v[214:217], v[198:201], v[28:31]
	v_mfma_f32_16x16x32_bf16 v[24:27], v[222:225], v[198:201], v[24:27]
	v_mfma_f32_16x16x32_bf16 v[12:15], v[214:217], v[206:209], v[12:15]
	v_mfma_f32_16x16x32_bf16 v[8:11], v[222:225], v[206:209], v[8:11]
	v_mfma_f32_16x16x32_bf16 v[60:63], v[218:221], v[186:189], v[60:63]
	v_mfma_f32_16x16x32_bf16 v[56:59], v[226:229], v[186:189], v[56:59]
	v_mfma_f32_16x16x32_bf16 v[44:47], v[218:221], v[194:197], v[44:47]
	v_mfma_f32_16x16x32_bf16 v[40:43], v[226:229], v[194:197], v[40:43]
	v_mfma_f32_16x16x32_bf16 v[28:31], v[218:221], v[202:205], v[28:31]
	v_mfma_f32_16x16x32_bf16 v[24:27], v[226:229], v[202:205], v[24:27]
	v_mfma_f32_16x16x32_bf16 v[12:15], v[218:221], v[210:213], v[12:15]
	v_mfma_f32_16x16x32_bf16 v[8:11], v[226:229], v[210:213], v[8:11]
	s_add_i32 s92, s92, 2
	s_add_u32 s30, s30, 0x100
	s_addc_u32 s31, s31, 0
	s_add_u32 s25, s25, 0x100
	s_addc_u32 s47, s47, 0
	s_cmp_gt_u32 s92, 13
	s_cbranch_scc1 .Lg1_exit
	s_branch .Lg1_head

.Lg1_epi:
	s_setprio 0
	s_nop 0
	s_nop 0
	s_nop 0
	s_nop 0
	s_nop 0
	s_nop 0
	s_nop 0
	s_waitcnt vmcnt(8)
	v_fmamk_f32 v132, v165, 0x3a800000, v235
	v_cmp_gt_f32_e32 vcc, s86, v132
	v_mul_f32_e32 v133, 0x4b800000, v132
	v_pk_mul_f32 v[126:127], v[118:119], v[126:127]
	v_cndmask_b32_e32 v132, v132, v133, vcc
	v_rsq_f32_e32 v132, v132
	v_pk_mul_f32 v[122:123], v[114:115], v[122:123]
	v_lshl_or_b32 v130, s0, 7, v157
	v_ashrrev_i32_e32 v131, 31, v130
	v_mul_f32_e32 v133, 0x45800000, v132
	v_cndmask_b32_e32 v132, v132, v133, vcc
	v_mul_f32_e32 v133, 0xbfb8aa3b, v132
	v_mul_f32_e32 v135, v133, v112
	v_exp_f32_e32 v135, v135
	v_mul_f32_e32 v134, v133, v116
	v_exp_f32_e32 v134, v134
	v_mul_f32_e32 v132, v132, v132
	v_add_f32_e32 v135, 1.0, v135
	v_rcp_f32_e32 v136, v135
	v_mul_f32_e32 v135, v133, v117
	v_exp_f32_e32 v135, v135
	v_add_f32_e32 v134, 1.0, v134
	v_rcp_f32_e32 v134, v134
	v_pk_mul_f32 v[116:117], v[116:117], v[124:125]
	v_add_f32_e32 v135, 1.0, v135
	v_rcp_f32_e32 v135, v135
	v_mul_f32_e32 v118, v133, v118
	v_mul_f32_e32 v119, v133, v119
	v_exp_f32_e32 v118, v118
	v_pk_mul_f32 v[124:125], v[132:133], v[134:135] op_sel_hi:[0,1]
	v_pk_mul_f32 v[116:117], v[124:125], v[116:117]
	v_mul_f32_e32 v124, v133, v113
	v_exp_f32_e32 v124, v124
	v_mul_f32_e32 v114, v133, v114
	v_exp_f32_e32 v119, v119
	v_mul_f32_e32 v115, v133, v115
	v_exp_f32_e32 v114, v114
	v_exp_f32_e32 v115, v115
	v_add_f32_e32 v124, 1.0, v124
	v_add_f32_e32 v118, 1.0, v118
	v_add_f32_e32 v119, 1.0, v119
	v_rcp_f32_e32 v137, v124
	v_rcp_f32_e32 v118, v118
	v_add_f32_e32 v114, 1.0, v114
	v_rcp_f32_e32 v119, v119
	v_add_f32_e32 v115, 1.0, v115
	v_rcp_f32_e32 v114, v114
	v_rcp_f32_e32 v115, v115
	v_pk_mul_f32 v[112:113], v[112:113], v[120:121]
	v_pk_mul_f32 v[120:121], v[132:133], v[136:137] op_sel_hi:[0,1]
	v_pk_mul_f32 v[118:119], v[132:133], v[118:119] op_sel_hi:[0,1]
	v_pk_mul_f32 v[112:113], v[120:121], v[112:113]
	v_pk_mul_f32 v[118:119], v[118:119], v[126:127]
	v_pk_mul_f32 v[114:115], v[132:133], v[114:115] op_sel_hi:[0,1]
	v_pk_mul_f32 v[114:115], v[114:115], v[122:123]
	v_cvt_pk_bf16_f32 v116, v116, v117
	v_cvt_pk_bf16_f32 v117, v118, v119
	v_cvt_pk_bf16_f32 v118, v112, v113
	v_mov_b64_e32 v[112:113], s[94:95]
	s_movk_i32 s9, 0x1600
	v_cvt_pk_bf16_f32 v119, v114, v115
	v_mad_i64_i32 v[120:121], s[0:1], v154, s9, v[112:113]
	v_lshlrev_b64 v[114:115], 1, v[130:131]
	v_lshl_add_u64 v[120:121], v[120:121], 0, v[114:115]
	global_store_dwordx4 v[120:121], v[116:119], off nt
	v_pk_mul_f32 v[106:107], v[98:99], v[106:107]
	v_pk_mul_f32 v[110:111], v[102:103], v[110:111]
	v_fmamk_f32 v116, v164, 0x3a800000, v235
	v_cmp_gt_f32_e32 vcc, s86, v116
	v_mul_f32_e32 v117, 0x4b800000, v116
	v_pk_mul_f32 v[90:91], v[82:83], v[90:91]
	v_cndmask_b32_e32 v116, v116, v117, vcc
	v_rsq_f32_e32 v116, v116
	v_pk_mul_f32 v[94:95], v[86:87], v[94:95]
	v_pk_mul_f32 v[74:75], v[66:67], v[74:75]
	v_pk_mul_f32 v[78:79], v[70:71], v[78:79]
	v_mul_f32_e32 v117, 0x45800000, v116
	v_cndmask_b32_e32 v116, v116, v117, vcc
	v_mul_f32_e32 v117, 0xbfb8aa3b, v116
	v_mul_f32_e32 v119, v117, v96
	v_exp_f32_e32 v119, v119
	v_mul_f32_e32 v118, v117, v100
	v_exp_f32_e32 v118, v118
	v_mul_f32_e32 v116, v116, v116
	v_add_f32_e32 v119, 1.0, v119
	v_rcp_f32_e32 v120, v119
	v_mul_f32_e32 v119, v117, v101
	v_exp_f32_e32 v119, v119
	v_add_f32_e32 v118, 1.0, v118
	v_rcp_f32_e32 v118, v118
	v_pk_mul_f32 v[100:101], v[100:101], v[108:109]
	v_add_f32_e32 v119, 1.0, v119
	v_rcp_f32_e32 v119, v119
	v_pk_mul_f32 v[58:59], v[50:51], v[58:59]
	v_pk_mul_f32 v[62:63], v[54:55], v[62:63]
	v_pk_mul_f32 v[42:43], v[34:35], v[42:43]
	v_pk_mul_f32 v[108:109], v[116:117], v[118:119] op_sel_hi:[0,1]
	v_pk_mul_f32 v[100:101], v[108:109], v[100:101]
	v_mul_f32_e32 v108, v117, v97
	v_exp_f32_e32 v108, v108
	v_pk_mul_f32 v[96:97], v[96:97], v[104:105]
	v_pk_mul_f32 v[46:47], v[38:39], v[46:47]
	v_pk_mul_f32 v[26:27], v[18:19], v[26:27]
	v_add_f32_e32 v108, 1.0, v108
	v_rcp_f32_e32 v121, v108
	v_or_b32_e32 v108, 16, v154
	v_pk_mul_f32 v[30:31], v[22:23], v[30:31]
	v_pk_mul_f32 v[10:11], v[2:3], v[10:11]
	v_pk_mul_f32 v[104:105], v[116:117], v[120:121] op_sel_hi:[0,1]
	v_pk_mul_f32 v[104:105], v[104:105], v[96:97]
	v_mul_f32_e32 v97, v117, v98
	v_exp_f32_e32 v97, v97
	v_mul_f32_e32 v96, v117, v102
	v_exp_f32_e32 v96, v96
	v_pk_mul_f32 v[14:15], v[6:7], v[14:15]
	v_add_f32_e32 v97, 1.0, v97
	v_rcp_f32_e32 v98, v97
	v_mul_f32_e32 v97, v117, v103
	v_exp_f32_e32 v97, v97
	v_add_f32_e32 v96, 1.0, v96
	v_rcp_f32_e32 v96, v96
	s_mov_b32 s20, s12
	v_add_f32_e32 v97, 1.0, v97
	v_rcp_f32_e32 v97, v97
	s_mov_b64 s[14:15], s[42:43]
	s_mov_b64 s[18:19], s[40:41]
	v_pk_mul_f32 v[96:97], v[116:117], v[96:97] op_sel_hi:[0,1]
	v_pk_mul_f32 v[102:103], v[96:97], v[110:111]
	v_mul_f32_e32 v96, v117, v99
	v_exp_f32_e32 v96, v96
	s_nop 0
	v_add_f32_e32 v96, 1.0, v96
	v_rcp_f32_e32 v99, v96
	s_nop 0
	v_pk_mul_f32 v[96:97], v[116:117], v[98:99] op_sel_hi:[0,1]
	v_pk_mul_f32 v[106:107], v[96:97], v[106:107]
	v_cvt_pk_bf16_f32 v96, v100, v101
	v_mad_i64_i32 v[100:101], s[0:1], v108, s9, v[112:113]
	v_cvt_pk_bf16_f32 v97, v102, v103
	v_cvt_pk_bf16_f32 v98, v104, v105
	v_cvt_pk_bf16_f32 v99, v106, v107
	v_lshl_add_u64 v[100:101], v[100:101], 0, v[114:115]
	global_store_dwordx4 v[100:101], v[96:99], off nt
	s_nop 1
	v_fmamk_f32 v96, v163, 0x3a800000, v235
	v_cmp_gt_f32_e32 vcc, s86, v96
	v_mul_f32_e32 v97, 0x4b800000, v96
	s_nop 0
	v_cndmask_b32_e32 v96, v96, v97, vcc
	v_rsq_f32_e32 v96, v96
	s_nop 0
	v_mul_f32_e32 v97, 0x45800000, v96
	v_cndmask_b32_e32 v96, v96, v97, vcc
	v_mul_f32_e32 v97, 0xbfb8aa3b, v96
	v_mul_f32_e32 v99, v97, v80
	v_exp_f32_e32 v99, v99
	v_mul_f32_e32 v98, v97, v84
	v_exp_f32_e32 v98, v98
	v_mul_f32_e32 v96, v96, v96
	v_add_f32_e32 v99, 1.0, v99
	v_rcp_f32_e32 v100, v99
	v_mul_f32_e32 v99, v97, v85
	v_exp_f32_e32 v99, v99
	v_add_f32_e32 v98, 1.0, v98
	v_rcp_f32_e32 v98, v98
	v_pk_mul_f32 v[84:85], v[84:85], v[92:93]
	v_add_f32_e32 v99, 1.0, v99
	v_rcp_f32_e32 v99, v99
	s_nop 0
	v_pk_mul_f32 v[92:93], v[96:97], v[98:99] op_sel_hi:[0,1]
	v_pk_mul_f32 v[84:85], v[92:93], v[84:85]
	v_mul_f32_e32 v92, v97, v81
	v_exp_f32_e32 v92, v92
	v_pk_mul_f32 v[80:81], v[80:81], v[88:89]
	v_add_f32_e32 v92, 1.0, v92
	v_rcp_f32_e32 v101, v92
	v_or_b32_e32 v92, 32, v154
	v_pk_mul_f32 v[88:89], v[96:97], v[100:101] op_sel_hi:[0,1]
	v_pk_mul_f32 v[88:89], v[88:89], v[80:81]
	v_mul_f32_e32 v81, v97, v82
	v_exp_f32_e32 v81, v81
	v_mul_f32_e32 v80, v97, v86
	v_exp_f32_e32 v80, v80
	v_add_f32_e32 v81, 1.0, v81
	v_rcp_f32_e32 v82, v81
	v_mul_f32_e32 v81, v97, v87
	v_exp_f32_e32 v81, v81
	v_add_f32_e32 v80, 1.0, v80
	v_rcp_f32_e32 v80, v80
	v_add_f32_e32 v81, 1.0, v81
	v_rcp_f32_e32 v81, v81
	s_nop 0
	v_pk_mul_f32 v[80:81], v[96:97], v[80:81] op_sel_hi:[0,1]
	v_pk_mul_f32 v[86:87], v[80:81], v[94:95]
	v_mul_f32_e32 v80, v97, v83
	v_exp_f32_e32 v80, v80
	s_nop 0
	v_add_f32_e32 v80, 1.0, v80
	v_rcp_f32_e32 v83, v80
	s_nop 0
	v_pk_mul_f32 v[80:81], v[96:97], v[82:83] op_sel_hi:[0,1]
	v_pk_mul_f32 v[90:91], v[80:81], v[90:91]
	v_cvt_pk_bf16_f32 v80, v84, v85
	v_mad_i64_i32 v[84:85], s[0:1], v92, s9, v[112:113]
	v_cvt_pk_bf16_f32 v81, v86, v87
	v_cvt_pk_bf16_f32 v82, v88, v89
	v_cvt_pk_bf16_f32 v83, v90, v91
	v_lshl_add_u64 v[84:85], v[84:85], 0, v[114:115]
	global_store_dwordx4 v[84:85], v[80:83], off nt
	s_nop 1
	v_fmamk_f32 v80, v162, 0x3a800000, v235
	v_cmp_gt_f32_e32 vcc, s86, v80
	v_mul_f32_e32 v81, 0x4b800000, v80
	s_nop 0
	v_cndmask_b32_e32 v80, v80, v81, vcc
	v_rsq_f32_e32 v80, v80
	s_nop 0
	v_mul_f32_e32 v81, 0x45800000, v80
	v_cndmask_b32_e32 v80, v80, v81, vcc
	v_mul_f32_e32 v81, 0xbfb8aa3b, v80
	v_mul_f32_e32 v83, v81, v64
	v_exp_f32_e32 v83, v83
	v_mul_f32_e32 v82, v81, v68
	v_exp_f32_e32 v82, v82
	v_mul_f32_e32 v80, v80, v80
	v_add_f32_e32 v83, 1.0, v83
	v_rcp_f32_e32 v84, v83
	v_mul_f32_e32 v83, v81, v69
	v_exp_f32_e32 v83, v83
	v_add_f32_e32 v82, 1.0, v82
	v_rcp_f32_e32 v82, v82
	v_pk_mul_f32 v[68:69], v[68:69], v[76:77]
	v_add_f32_e32 v83, 1.0, v83
	v_rcp_f32_e32 v83, v83
	s_nop 0
	v_pk_mul_f32 v[76:77], v[80:81], v[82:83] op_sel_hi:[0,1]
	v_pk_mul_f32 v[68:69], v[76:77], v[68:69]
	v_mul_f32_e32 v76, v81, v65
	v_exp_f32_e32 v76, v76
	v_pk_mul_f32 v[64:65], v[64:65], v[72:73]
	v_add_f32_e32 v76, 1.0, v76
	v_rcp_f32_e32 v85, v76
	v_or_b32_e32 v76, 48, v154
	v_pk_mul_f32 v[72:73], v[80:81], v[84:85] op_sel_hi:[0,1]
	v_pk_mul_f32 v[72:73], v[72:73], v[64:65]
	v_mul_f32_e32 v65, v81, v66
	v_exp_f32_e32 v65, v65
	v_mul_f32_e32 v64, v81, v70
	v_exp_f32_e32 v64, v64
	v_add_f32_e32 v65, 1.0, v65
	v_rcp_f32_e32 v66, v65
	v_mul_f32_e32 v65, v81, v71
	v_exp_f32_e32 v65, v65
	v_add_f32_e32 v64, 1.0, v64
	v_rcp_f32_e32 v64, v64
	v_add_f32_e32 v65, 1.0, v65
	v_rcp_f32_e32 v65, v65
	s_nop 0
	v_pk_mul_f32 v[64:65], v[80:81], v[64:65] op_sel_hi:[0,1]
	v_pk_mul_f32 v[70:71], v[64:65], v[78:79]
	v_mul_f32_e32 v64, v81, v67
	v_exp_f32_e32 v64, v64
	s_nop 0
	v_add_f32_e32 v64, 1.0, v64
	v_rcp_f32_e32 v67, v64
	s_nop 0
	v_pk_mul_f32 v[64:65], v[80:81], v[66:67] op_sel_hi:[0,1]
	v_pk_mul_f32 v[74:75], v[64:65], v[74:75]
	v_cvt_pk_bf16_f32 v64, v68, v69
	v_mad_i64_i32 v[68:69], s[0:1], v76, s9, v[112:113]
	v_cvt_pk_bf16_f32 v65, v70, v71
	v_cvt_pk_bf16_f32 v66, v72, v73
	v_cvt_pk_bf16_f32 v67, v74, v75
	v_lshl_add_u64 v[68:69], v[68:69], 0, v[114:115]
	global_store_dwordx4 v[68:69], v[64:67], off nt
	s_nop 1
	v_fmamk_f32 v64, v161, 0x3a800000, v235
	v_cmp_gt_f32_e32 vcc, s86, v64
	v_mul_f32_e32 v66, 0x4b800000, v64
	v_add_u32_e32 v65, 0x80, v154
	v_cndmask_b32_e32 v64, v64, v66, vcc
	v_rsq_f32_e32 v64, v64
	s_nop 0
	v_mul_f32_e32 v66, 0x45800000, v64
	v_cndmask_b32_e32 v64, v64, v66, vcc
	v_mul_f32_e32 v70, 0xbfb8aa3b, v64
	v_mul_f32_e32 v67, v70, v48
	v_exp_f32_e32 v67, v67
	v_mul_f32_e32 v66, v70, v52
	v_exp_f32_e32 v66, v66
	v_mul_f32_e32 v64, v64, v64
	v_add_f32_e32 v67, 1.0, v67
	v_rcp_f32_e32 v68, v67
	v_mul_f32_e32 v67, v70, v53
	v_exp_f32_e32 v67, v67
	v_add_f32_e32 v66, 1.0, v66
	v_rcp_f32_e32 v66, v66
	v_pk_mul_f32 v[52:53], v[52:53], v[60:61]
	v_add_f32_e32 v67, 1.0, v67
	v_rcp_f32_e32 v67, v67
	s_nop 0
	v_pk_mul_f32 v[60:61], v[64:65], v[66:67] op_sel_hi:[0,1]
	v_pk_mul_f32 v[52:53], v[60:61], v[52:53]
	v_mul_f32_e32 v60, v70, v49
	v_exp_f32_e32 v60, v60
	v_pk_mul_f32 v[48:49], v[48:49], v[56:57]
	v_add_f32_e32 v60, 1.0, v60
	v_rcp_f32_e32 v69, v60
	s_nop 0
	v_pk_mul_f32 v[56:57], v[64:65], v[68:69] op_sel_hi:[0,1]
	v_pk_mul_f32 v[56:57], v[56:57], v[48:49]
	v_mul_f32_e32 v49, v70, v50
	v_exp_f32_e32 v49, v49
	v_mul_f32_e32 v48, v70, v54
	v_exp_f32_e32 v48, v48
	v_add_f32_e32 v49, 1.0, v49
	v_rcp_f32_e32 v50, v49
	v_mul_f32_e32 v49, v70, v55
	v_exp_f32_e32 v49, v49
	v_add_f32_e32 v48, 1.0, v48
	v_rcp_f32_e32 v48, v48
	v_add_f32_e32 v49, 1.0, v49
	v_rcp_f32_e32 v49, v49
	s_nop 0
	v_pk_mul_f32 v[48:49], v[64:65], v[48:49] op_sel_hi:[0,1]
	v_pk_mul_f32 v[54:55], v[48:49], v[62:63]
	v_mul_f32_e32 v48, v70, v51
	v_exp_f32_e32 v48, v48
	s_nop 0
	v_add_f32_e32 v48, 1.0, v48
	v_rcp_f32_e32 v51, v48
	s_nop 0
	v_pk_mul_f32 v[48:49], v[64:65], v[50:51] op_sel_hi:[0,1]
	v_pk_mul_f32 v[58:59], v[48:49], v[58:59]
	v_cvt_pk_bf16_f32 v48, v52, v53
	v_mad_i64_i32 v[52:53], s[0:1], v65, s9, v[112:113]
	v_cvt_pk_bf16_f32 v49, v54, v55
	v_cvt_pk_bf16_f32 v50, v56, v57
	v_cvt_pk_bf16_f32 v51, v58, v59
	v_lshl_add_u64 v[52:53], v[52:53], 0, v[114:115]
	global_store_dwordx4 v[52:53], v[48:51], off nt
	s_nop 1
	v_fmamk_f32 v48, v160, 0x3a800000, v235
	v_cmp_gt_f32_e32 vcc, s86, v48
	v_mul_f32_e32 v49, 0x4b800000, v48
	s_nop 0
	v_cndmask_b32_e32 v48, v48, v49, vcc
	v_rsq_f32_e32 v48, v48
	s_nop 0
	v_mul_f32_e32 v49, 0x45800000, v48
	v_cndmask_b32_e32 v48, v48, v49, vcc
	v_mul_f32_e32 v49, 0xbfb8aa3b, v48
	v_mul_f32_e32 v51, v49, v32
	v_exp_f32_e32 v51, v51
	v_mul_f32_e32 v50, v49, v36
	v_exp_f32_e32 v50, v50
	v_mul_f32_e32 v48, v48, v48
	v_add_f32_e32 v51, 1.0, v51
	v_rcp_f32_e32 v52, v51
	v_mul_f32_e32 v51, v49, v37
	v_exp_f32_e32 v51, v51
	v_add_f32_e32 v50, 1.0, v50
	v_rcp_f32_e32 v50, v50
	v_pk_mul_f32 v[36:37], v[36:37], v[44:45]
	v_add_f32_e32 v51, 1.0, v51
	v_rcp_f32_e32 v51, v51
	s_nop 0
	v_pk_mul_f32 v[44:45], v[48:49], v[50:51] op_sel_hi:[0,1]
	v_pk_mul_f32 v[36:37], v[44:45], v[36:37]
	v_mul_f32_e32 v44, v49, v33
	v_exp_f32_e32 v44, v44
	v_pk_mul_f32 v[32:33], v[32:33], v[40:41]
	v_add_f32_e32 v44, 1.0, v44
	v_rcp_f32_e32 v53, v44
	v_add_u32_e32 v44, 0x90, v154
	v_pk_mul_f32 v[40:41], v[48:49], v[52:53] op_sel_hi:[0,1]
	v_pk_mul_f32 v[40:41], v[40:41], v[32:33]
	v_mul_f32_e32 v33, v49, v34
	v_exp_f32_e32 v33, v33
	v_mul_f32_e32 v32, v49, v38
	v_exp_f32_e32 v32, v32
	v_add_f32_e32 v33, 1.0, v33
	v_rcp_f32_e32 v34, v33
	v_mul_f32_e32 v33, v49, v39
	v_exp_f32_e32 v33, v33
	v_add_f32_e32 v32, 1.0, v32
	v_rcp_f32_e32 v32, v32
	v_add_f32_e32 v33, 1.0, v33
	v_rcp_f32_e32 v33, v33
	s_nop 0
	v_pk_mul_f32 v[32:33], v[48:49], v[32:33] op_sel_hi:[0,1]
	v_pk_mul_f32 v[38:39], v[32:33], v[46:47]
	v_mul_f32_e32 v32, v49, v35
	v_exp_f32_e32 v32, v32
	s_nop 0
	v_add_f32_e32 v32, 1.0, v32
	v_rcp_f32_e32 v35, v32
	s_nop 0
	v_pk_mul_f32 v[32:33], v[48:49], v[34:35] op_sel_hi:[0,1]
	v_pk_mul_f32 v[42:43], v[32:33], v[42:43]
	v_cvt_pk_bf16_f32 v32, v36, v37
	v_mad_i64_i32 v[36:37], s[0:1], v44, s9, v[112:113]
	v_cvt_pk_bf16_f32 v33, v38, v39
	v_cvt_pk_bf16_f32 v34, v40, v41
	v_cvt_pk_bf16_f32 v35, v42, v43
	v_lshl_add_u64 v[36:37], v[36:37], 0, v[114:115]
	global_store_dwordx4 v[36:37], v[32:35], off nt
	s_nop 1
	v_fmamk_f32 v32, v159, 0x3a800000, v235
	v_cmp_gt_f32_e32 vcc, s86, v32
	v_mul_f32_e32 v33, 0x4b800000, v32
	s_nop 0
	v_cndmask_b32_e32 v32, v32, v33, vcc
	v_rsq_f32_e32 v32, v32
	s_nop 0
	v_mul_f32_e32 v33, 0x45800000, v32
	v_cndmask_b32_e32 v32, v32, v33, vcc
	v_mul_f32_e32 v33, 0xbfb8aa3b, v32
	v_mul_f32_e32 v35, v33, v16
	v_exp_f32_e32 v35, v35
	v_mul_f32_e32 v34, v33, v20
	v_exp_f32_e32 v34, v34
	v_mul_f32_e32 v32, v32, v32
	v_add_f32_e32 v35, 1.0, v35
	v_rcp_f32_e32 v36, v35
	v_mul_f32_e32 v35, v33, v21
	v_exp_f32_e32 v35, v35
	v_add_f32_e32 v34, 1.0, v34
	v_rcp_f32_e32 v34, v34
	v_pk_mul_f32 v[20:21], v[20:21], v[28:29]
	v_add_f32_e32 v35, 1.0, v35
	v_rcp_f32_e32 v35, v35
	s_nop 0
	v_pk_mul_f32 v[28:29], v[32:33], v[34:35] op_sel_hi:[0,1]
	v_pk_mul_f32 v[20:21], v[28:29], v[20:21]
	v_mul_f32_e32 v28, v33, v17
	v_exp_f32_e32 v28, v28
	v_pk_mul_f32 v[16:17], v[16:17], v[24:25]
	v_add_f32_e32 v28, 1.0, v28
	v_rcp_f32_e32 v37, v28
	v_add_u32_e32 v28, 0xa0, v154
	v_pk_mul_f32 v[24:25], v[32:33], v[36:37] op_sel_hi:[0,1]
	v_pk_mul_f32 v[24:25], v[24:25], v[16:17]
	v_mul_f32_e32 v17, v33, v18
	v_exp_f32_e32 v17, v17
	v_mul_f32_e32 v16, v33, v22
	v_exp_f32_e32 v16, v16
	v_add_f32_e32 v17, 1.0, v17
	v_rcp_f32_e32 v18, v17
	v_mul_f32_e32 v17, v33, v23
	v_exp_f32_e32 v17, v17
	v_add_f32_e32 v16, 1.0, v16
	v_rcp_f32_e32 v16, v16
	v_add_f32_e32 v17, 1.0, v17
	v_rcp_f32_e32 v17, v17
	s_nop 0
	v_pk_mul_f32 v[16:17], v[32:33], v[16:17] op_sel_hi:[0,1]
	v_pk_mul_f32 v[22:23], v[16:17], v[30:31]
	v_mul_f32_e32 v16, v33, v19
	v_exp_f32_e32 v16, v16
	s_nop 0
	v_add_f32_e32 v16, 1.0, v16
	v_rcp_f32_e32 v19, v16
	s_nop 0
	v_pk_mul_f32 v[16:17], v[32:33], v[18:19] op_sel_hi:[0,1]
	v_pk_mul_f32 v[26:27], v[16:17], v[26:27]
	v_cvt_pk_bf16_f32 v16, v20, v21
	v_mad_i64_i32 v[20:21], s[0:1], v28, s9, v[112:113]
	v_cvt_pk_bf16_f32 v17, v22, v23
	v_cvt_pk_bf16_f32 v18, v24, v25
	v_cvt_pk_bf16_f32 v19, v26, v27
	v_lshl_add_u64 v[20:21], v[20:21], 0, v[114:115]
	global_store_dwordx4 v[20:21], v[16:19], off nt
	s_nop 1
	v_fmamk_f32 v16, v155, 0x3a800000, v235
	v_cmp_gt_f32_e32 vcc, s86, v16
	v_mul_f32_e32 v17, 0x4b800000, v16
	s_nop 0
	v_cndmask_b32_e32 v16, v16, v17, vcc
	v_rsq_f32_e32 v16, v16
	s_nop 0
	v_mul_f32_e32 v17, 0x45800000, v16
	v_cndmask_b32_e32 v16, v16, v17, vcc
	v_mul_f32_e32 v17, 0xbfb8aa3b, v16
	v_mul_f32_e32 v19, v17, v0
	v_exp_f32_e32 v19, v19
	v_mul_f32_e32 v18, v17, v4
	v_exp_f32_e32 v18, v18
	v_mul_f32_e32 v16, v16, v16
	v_add_f32_e32 v19, 1.0, v19
	v_rcp_f32_e32 v20, v19
	v_mul_f32_e32 v19, v17, v5
	v_exp_f32_e32 v19, v19
	v_add_f32_e32 v18, 1.0, v18
	v_rcp_f32_e32 v18, v18
	v_pk_mul_f32 v[4:5], v[4:5], v[12:13]
	v_add_f32_e32 v19, 1.0, v19
	v_rcp_f32_e32 v19, v19
	s_and_b64 vcc, exec, s[38:39]
	v_pk_mul_f32 v[12:13], v[16:17], v[18:19] op_sel_hi:[0,1]
	v_pk_mul_f32 v[4:5], v[12:13], v[4:5]
	v_mul_f32_e32 v12, v17, v1
	v_exp_f32_e32 v12, v12
	v_pk_mul_f32 v[0:1], v[0:1], v[8:9]
	v_add_f32_e32 v12, 1.0, v12
	v_rcp_f32_e32 v21, v12
	v_add_u32_e32 v12, 0xb0, v154
	v_pk_mul_f32 v[8:9], v[16:17], v[20:21] op_sel_hi:[0,1]
	v_pk_mul_f32 v[8:9], v[8:9], v[0:1]
	v_mul_f32_e32 v1, v17, v2
	v_exp_f32_e32 v1, v1
	v_mul_f32_e32 v0, v17, v6
	v_exp_f32_e32 v0, v0
	v_add_f32_e32 v1, 1.0, v1
	v_rcp_f32_e32 v2, v1
	v_mul_f32_e32 v1, v17, v7
	v_exp_f32_e32 v1, v1
	v_add_f32_e32 v0, 1.0, v0
	v_rcp_f32_e32 v0, v0
	v_add_f32_e32 v1, 1.0, v1
	v_rcp_f32_e32 v1, v1
	s_nop 0
	v_pk_mul_f32 v[0:1], v[16:17], v[0:1] op_sel_hi:[0,1]
	v_pk_mul_f32 v[6:7], v[0:1], v[14:15]
	v_mul_f32_e32 v0, v17, v3
	v_exp_f32_e32 v0, v0
	s_nop 0
	v_add_f32_e32 v0, 1.0, v0
	v_rcp_f32_e32 v3, v0
	s_nop 0
	v_pk_mul_f32 v[0:1], v[16:17], v[2:3] op_sel_hi:[0,1]
	v_pk_mul_f32 v[10:11], v[0:1], v[10:11]
	v_cvt_pk_bf16_f32 v0, v4, v5
	v_mad_i64_i32 v[4:5], s[0:1], v12, s9, v[112:113]
	v_cvt_pk_bf16_f32 v1, v6, v7
	v_cvt_pk_bf16_f32 v2, v8, v9
	v_cvt_pk_bf16_f32 v3, v10, v11
	v_lshl_add_u64 v[4:5], v[4:5], 0, v[114:115]
	s_mov_b32 s0, s8
	global_store_dwordx4 v[4:5], v[0:3], off nt
	s_cbranch_vccz .LBB0_388
	s_waitcnt vmcnt(0)
	v_readlane_b32 s20, v255, 27
